# GEMM K-loops: redundant s_setprio 0/1 pair removed from the middle of each 32-MFMA block
# speedup vs baseline: 1.0029x; 1.0029x over previous
; #define PG8_STAGE(bufoff, gbase) do { _Pragma("unroll") for (int _i = 0; _i < 2; ++_i) \
;         __builtin_amdgcn_global_load_lds((const unsigned*)((const char*)(gbase) + voffA[_i]), (LAS unsigned*)(lds + (bufoff) + ldsw + _i * 8192), 16, 0, 0); } while (0)
; #define PG8_LDA(dst, b, h) do { _Pragma("unroll") for (int m = 0; m < 4; ++m) _Pragma("unroll") for (int k = 0; k < 2; ++k) dst[m][k] = *(const LAS bf16x8*)(lds + PG8_SA(b, h) + aoff + m * 2048 + k * 1024); } while (0)
; #define PG8_LDB(dst, b, h) do { _Pragma("unroll") for (int n = 0; n < 2; ++n) _Pragma("unroll") for (int k = 0; k < 2; ++k) dst[n][k] = *(const LAS bf16x8*)(lds + PG8_SB(b, h) + boff + n * 2048 + k * 1024); } while (0)
; #define PG8_MMA(ai, bj, At, Bt) do { __builtin_amdgcn_s_setprio(1); _Pragma("unroll") for (int m = 0; m < 4; ++m) _Pragma("unroll") for (int n = 0; n < 2; ++n) _Pragma("unroll") for (int k = 0; k < 2; ++k) \
;         acc[ai][bj][m][n] = __builtin_amdgcn_mfma_f32_16x16x32_bf16(Bt[n][k], At[m][k], acc[ai][bj][m][n], 0, 0, 0); __builtin_amdgcn_s_setprio(0); } while (0)
; #define PG8_WAIT_V(n) asm volatile("s_waitcnt vmcnt(" #n ")" ::: "memory")
; #define PG8_WAIT_L(n) asm volatile("s_waitcnt lgkmcnt(" #n ")" ::: "memory")
; #define PG8_BAR __builtin_amdgcn_s_barrier()
; #define PG8_SCHED __builtin_amdgcn_sched_barrier(0)
; template <class Epi, class Sched>
; __device__ __forceinline__ void gemm_phase(LAS unsigned char* lds, const Gemm g, const Sched& S, const Epi& E) {
;     ...
;         for (int t = 0; t < nt; t += 2) {
;             const bool last = (t == nt - 2);
;             const char* a1 = cA + (size_t)(t + 1) * kstep;
;             const char* a2 = last ? nA : cA + (size_t)(t + 2) * kstep; const char* b2 = last ? nB : cB + (size_t)(t + 2) * kstep;
;             const char* a3 = a2 + kstep; const char* b3 = b2 + kstep;
;             PG8_LDB(B0, 0, 0); PG8_LDB(B1, 0, 1); PG8_SCHED; PG8_LDA(At, 0, 0); PG8_STAGE(PG8_SA(1, 1), a1 + hstep);
;             PG8_WAIT_V(8); PG8_WAIT_L(0); PG8_BAR; PG8_MMA(0, 0, At, B0); PG8_MMA(0, 1, At, B1); PG8_BAR; PG8_SCHED;
;             PG8_LDA(At, 0, 1); PG8_STAGE(PG8_SB(0, 0), b2); PG8_STAGE(PG8_SB(0, 1), b2 + hstep); PG8_STAGE(PG8_SA(0, 0), a2);
;             PG8_WAIT_V(8); PG8_WAIT_L(0); PG8_BAR; PG8_MMA(1, 0, At, B0); PG8_MMA(1, 1, At, B1); PG8_BAR; PG8_SCHED;
.LBB0_51:
	s_add_u32 s64, s62, 0xfff80080
	s_addc_u32 s65, s63, -1
	s_add_i32 s91, 0, 0x10000
	s_cmp_eq_u32 s90, 28
	s_cselect_b32 s67, s47, s65
	s_cselect_b32 s66, s84, s64
	v_add_u32_e32 v136, s91, v139
	s_cselect_b32 s65, s45, s89
	s_cselect_b32 s64, s85, s88
	s_add_i32 s94, 0, 0x14000
	ds_read_b128 v[142:145], v136
	ds_read_b128 v[164:167], v136 offset:1024
	ds_read_b128 v[168:171], v136 offset:2048
	ds_read_b128 v[172:175], v136 offset:3072
	v_add_u32_e32 v136, s94, v139
	ds_read_b128 v[176:179], v136
	ds_read_b128 v[180:183], v136 offset:1024
	ds_read_b128 v[184:187], v136 offset:2048
	ds_read_b128 v[188:191], v136 offset:3072
	v_lshl_add_u64 v[136:137], s[62:63], 0, v[132:133]
	s_add_i32 m0, s69, 0xc000
	ds_read_b128 v[192:195], v141
	ds_read_b128 v[196:199], v141 offset:1024
	ds_read_b128 v[200:203], v141 offset:2048
	ds_read_b128 v[204:207], v141 offset:3072
	ds_read_b128 v[208:211], v141 offset:4096
	ds_read_b128 v[222:225], v141 offset:5120
	ds_read_b128 v[226:229], v141 offset:6144
	ds_read_b128 v[230:233], v141 offset:7168
	global_load_lds_dwordx4 v[136:137], off
	v_lshl_add_u64 v[136:137], s[62:63], 0, v[134:135]
	s_add_i32 m0, s69, 0xe000
	s_nop 0
	global_load_lds_dwordx4 v[136:137], off
	s_waitcnt vmcnt(8)
	s_waitcnt lgkmcnt(0)
	s_barrier
	s_setprio 1
	s_waitcnt lgkmcnt(0)
	v_mfma_f32_16x16x32_bf16 v[126:129], v[142:145], v[192:195], v[126:129]
	v_mfma_f32_16x16x32_bf16 v[118:121], v[168:171], v[192:195], v[118:121]
	v_mfma_f32_16x16x32_bf16 v[110:113], v[142:145], v[200:203], v[110:113]
	v_mfma_f32_16x16x32_bf16 v[102:105], v[168:171], v[200:203], v[102:105]
	v_mfma_f32_16x16x32_bf16 v[94:97], v[142:145], v[208:211], v[94:97]
	v_mfma_f32_16x16x32_bf16 v[86:89], v[168:171], v[208:211], v[86:89]
	v_mfma_f32_16x16x32_bf16 v[78:81], v[142:145], v[226:229], v[78:81]
	v_mfma_f32_16x16x32_bf16 v[70:73], v[168:171], v[226:229], v[70:73]
	v_mfma_f32_16x16x32_bf16 v[126:129], v[164:167], v[196:199], v[126:129]
	v_mfma_f32_16x16x32_bf16 v[118:121], v[172:175], v[196:199], v[118:121]
	v_mfma_f32_16x16x32_bf16 v[110:113], v[164:167], v[204:207], v[110:113]
	v_mfma_f32_16x16x32_bf16 v[102:105], v[172:175], v[204:207], v[102:105]
	v_mfma_f32_16x16x32_bf16 v[94:97], v[164:167], v[222:225], v[94:97]
	v_mfma_f32_16x16x32_bf16 v[86:89], v[172:175], v[222:225], v[86:89]
	v_mfma_f32_16x16x32_bf16 v[78:81], v[164:167], v[230:233], v[78:81]
	v_mfma_f32_16x16x32_bf16 v[70:73], v[172:175], v[230:233], v[70:73]
	v_mfma_f32_16x16x32_bf16 v[122:125], v[176:179], v[192:195], v[122:125]
	v_mfma_f32_16x16x32_bf16 v[114:117], v[184:187], v[192:195], v[114:117]
	v_mfma_f32_16x16x32_bf16 v[106:109], v[176:179], v[200:203], v[106:109]
	v_mfma_f32_16x16x32_bf16 v[98:101], v[184:187], v[200:203], v[98:101]
	v_mfma_f32_16x16x32_bf16 v[90:93], v[176:179], v[208:211], v[90:93]
	v_mfma_f32_16x16x32_bf16 v[82:85], v[184:187], v[208:211], v[82:85]
	v_mfma_f32_16x16x32_bf16 v[74:77], v[176:179], v[226:229], v[74:77]
	v_mfma_f32_16x16x32_bf16 v[66:69], v[184:187], v[226:229], v[66:69]
	v_mfma_f32_16x16x32_bf16 v[122:125], v[180:183], v[196:199], v[122:125]
	v_mfma_f32_16x16x32_bf16 v[114:117], v[188:191], v[196:199], v[114:117]
	v_mfma_f32_16x16x32_bf16 v[106:109], v[180:183], v[204:207], v[106:109]
	v_mfma_f32_16x16x32_bf16 v[98:101], v[188:191], v[204:207], v[98:101]
	v_mfma_f32_16x16x32_bf16 v[90:93], v[180:183], v[222:225], v[90:93]
	v_mfma_f32_16x16x32_bf16 v[82:85], v[188:191], v[222:225], v[82:85]
	v_mfma_f32_16x16x32_bf16 v[74:77], v[180:183], v[230:233], v[74:77]
	v_mfma_f32_16x16x32_bf16 v[66:69], v[188:191], v[230:233], v[66:69]
	s_setprio 0
	s_barrier
	s_add_i32 s91, s91, s57
	v_lshl_add_u64 v[136:137], s[64:65], 0, v[0:1]
	s_mov_b32 m0, s91
	ds_read_b128 v[192:195], v141 offset:16384
	ds_read_b128 v[196:199], v141 offset:17408
	ds_read_b128 v[200:203], v141 offset:18432
	ds_read_b128 v[204:207], v141 offset:19456
	ds_read_b128 v[208:211], v141 offset:20480
	ds_read_b128 v[222:225], v141 offset:21504
	ds_read_b128 v[226:229], v141 offset:22528
	ds_read_b128 v[230:233], v141 offset:23552
	global_load_lds_dwordx4 v[136:137], off
	s_add_i32 m0, s91, 0x2000
	s_add_u32 s92, s64, 0x80000
	v_lshl_add_u64 v[234:235], s[64:65], 0, v[130:131]
	s_addc_u32 s93, s65, 0
	s_add_i32 s91, s94, s57
	global_load_lds_dwordx4 v[234:235], off
	v_lshl_add_u64 v[236:237], s[92:93], 0, v[0:1]
	s_mov_b32 m0, s91
	v_lshl_add_u64 v[238:239], s[66:67], 0, v[130:131]
	global_load_lds_dwordx4 v[236:237], off
	v_lshl_add_u64 v[236:237], s[92:93], 0, v[130:131]
	s_add_i32 m0, s91, 0x2000
	s_nop 0
	global_load_lds_dwordx4 v[236:237], off
	v_lshl_add_u64 v[236:237], s[66:67], 0, v[0:1]
	s_mov_b32 m0, s69
	s_nop 0
	global_load_lds_dwordx4 v[236:237], off
	s_mov_b32 m0, s70
	s_nop 0
	global_load_lds_dwordx4 v[238:239], off
	s_waitcnt vmcnt(8)
	s_waitcnt lgkmcnt(0)
	s_barrier
; #define PG8_STAGE(bufoff, gbase) do { _Pragma("unroll") for (int _i = 0; _i < 2; ++_i) \
;         __builtin_amdgcn_global_load_lds((const unsigned*)((const char*)(gbase) + voffA[_i]), (LAS unsigned*)(lds + (bufoff) + ldsw + _i * 8192), 16, 0, 0); } while (0)
; #define PG8_LDA(dst, b, h) do { _Pragma("unroll") for (int m = 0; m < 4; ++m) _Pragma("unroll") for (int k = 0; k < 2; ++k) dst[m][k] = *(const LAS bf16x8*)(lds + PG8_SA(b, h) + aoff + m * 2048 + k * 1024); } while (0)
; #define PG8_LDB(dst, b, h) do { _Pragma("unroll") for (int n = 0; n < 2; ++n) _Pragma("unroll") for (int k = 0; k < 2; ++k) dst[n][k] = *(const LAS bf16x8*)(lds + PG8_SB(b, h) + boff + n * 2048 + k * 1024); } while (0)
; #define PG8_MMA(ai, bj, At, Bt) do { __builtin_amdgcn_s_setprio(1); _Pragma("unroll") for (int m = 0; m < 4; ++m) _Pragma("unroll") for (int n = 0; n < 2; ++n) _Pragma("unroll") for (int k = 0; k < 2; ++k) \
;         acc[ai][bj][m][n] = __builtin_amdgcn_mfma_f32_16x16x32_bf16(Bt[n][k], At[m][k], acc[ai][bj][m][n], 0, 0, 0); __builtin_amdgcn_s_setprio(0); } while (0)
; #define PG8_WAIT_V(n) asm volatile("s_waitcnt vmcnt(" #n ")" ::: "memory")
; #define PG8_WAIT_L(n) asm volatile("s_waitcnt lgkmcnt(" #n ")" ::: "memory")
; #define PG8_BAR __builtin_amdgcn_s_barrier()
; #define PG8_SCHED __builtin_amdgcn_sched_barrier(0)
; template <class Epi, class Sched>
; __device__ __forceinline__ void gemm_phase(LAS unsigned char* lds, const Gemm g, const Sched& S, const Epi& E) {
;     ...
;             PG8_WAIT_V(8); PG8_WAIT_L(0); PG8_BAR; PG8_MMA(1, 0, At, B0); PG8_MMA(1, 1, At, B1); PG8_BAR; PG8_SCHED;
;             PG8_LDB(B0, 1, 0); PG8_LDB(B1, 1, 1); PG8_SCHED; PG8_LDA(At, 1, 0); PG8_STAGE(PG8_SA(0, 1), a2 + hstep);
;             PG8_WAIT_V(8); PG8_WAIT_L(0); PG8_BAR; PG8_MMA(0, 0, At, B0); PG8_MMA(0, 1, At, B1); PG8_BAR; PG8_SCHED;
	s_setprio 1
	s_waitcnt lgkmcnt(0)
	v_mfma_f32_16x16x32_bf16 v[62:65], v[142:145], v[192:195], v[62:65]
	v_mfma_f32_16x16x32_bf16 v[54:57], v[168:171], v[192:195], v[54:57]
	v_mfma_f32_16x16x32_bf16 v[46:49], v[142:145], v[200:203], v[46:49]
	v_mfma_f32_16x16x32_bf16 v[38:41], v[168:171], v[200:203], v[38:41]
	v_mfma_f32_16x16x32_bf16 v[30:33], v[142:145], v[208:211], v[30:33]
	v_mfma_f32_16x16x32_bf16 v[22:25], v[168:171], v[208:211], v[22:25]
	v_mfma_f32_16x16x32_bf16 v[14:17], v[142:145], v[226:229], v[14:17]
	v_mfma_f32_16x16x32_bf16 v[6:9], v[168:171], v[226:229], v[6:9]
	v_mfma_f32_16x16x32_bf16 v[62:65], v[164:167], v[196:199], v[62:65]
	v_mfma_f32_16x16x32_bf16 v[54:57], v[172:175], v[196:199], v[54:57]
	v_mfma_f32_16x16x32_bf16 v[46:49], v[164:167], v[204:207], v[46:49]
	v_mfma_f32_16x16x32_bf16 v[38:41], v[172:175], v[204:207], v[38:41]
	v_mfma_f32_16x16x32_bf16 v[30:33], v[164:167], v[222:225], v[30:33]
	v_mfma_f32_16x16x32_bf16 v[22:25], v[172:175], v[222:225], v[22:25]
	v_mfma_f32_16x16x32_bf16 v[14:17], v[164:167], v[230:233], v[14:17]
	v_mfma_f32_16x16x32_bf16 v[6:9], v[172:175], v[230:233], v[6:9]
	v_mfma_f32_16x16x32_bf16 v[58:61], v[176:179], v[192:195], v[58:61]
	v_mfma_f32_16x16x32_bf16 v[50:53], v[184:187], v[192:195], v[50:53]
	v_mfma_f32_16x16x32_bf16 v[42:45], v[176:179], v[200:203], v[42:45]
	v_mfma_f32_16x16x32_bf16 v[34:37], v[184:187], v[200:203], v[34:37]
	v_mfma_f32_16x16x32_bf16 v[26:29], v[176:179], v[208:211], v[26:29]
	v_mfma_f32_16x16x32_bf16 v[18:21], v[184:187], v[208:211], v[18:21]
	v_mfma_f32_16x16x32_bf16 v[10:13], v[176:179], v[226:229], v[10:13]
	v_mfma_f32_16x16x32_bf16 v[2:5], v[184:187], v[226:229], v[2:5]
	v_mfma_f32_16x16x32_bf16 v[58:61], v[180:183], v[196:199], v[58:61]
	v_mfma_f32_16x16x32_bf16 v[50:53], v[188:191], v[196:199], v[50:53]
	v_mfma_f32_16x16x32_bf16 v[42:45], v[180:183], v[204:207], v[42:45]
	v_mfma_f32_16x16x32_bf16 v[34:37], v[188:191], v[204:207], v[34:37]
	v_mfma_f32_16x16x32_bf16 v[26:29], v[180:183], v[222:225], v[26:29]
	v_mfma_f32_16x16x32_bf16 v[18:21], v[188:191], v[222:225], v[18:21]
	v_mfma_f32_16x16x32_bf16 v[10:13], v[180:183], v[230:233], v[10:13]
	v_mfma_f32_16x16x32_bf16 v[2:5], v[188:191], v[230:233], v[2:5]
	s_setprio 0
	s_barrier
	s_add_i32 s91, 0, 0x1c000
	v_add_u32_e32 v172, s99, v139
	v_add_u32_e32 v188, s91, v139
	ds_read_b128 v[142:145], v172
	ds_read_b128 v[164:167], v172 offset:1024
	ds_read_b128 v[168:171], v172 offset:2048
	ds_read_b128 v[172:175], v172 offset:3072
	ds_read_b128 v[176:179], v188
	ds_read_b128 v[180:183], v188 offset:1024
	ds_read_b128 v[184:187], v188 offset:2048
	ds_read_b128 v[188:191], v188 offset:3072
	s_add_u32 s66, s66, 0x80000
	s_addc_u32 s67, s67, 0
	s_mov_b32 m0, s71
	v_lshl_add_u64 v[240:241], s[66:67], 0, v[0:1]
	ds_read_b128 v[192:195], v141 offset:32768
	ds_read_b128 v[196:199], v141 offset:33792
	ds_read_b128 v[200:203], v141 offset:34816
	ds_read_b128 v[204:207], v141 offset:35840
	ds_read_b128 v[208:211], v141 offset:36864
	ds_read_b128 v[222:225], v141 offset:37888
	ds_read_b128 v[226:229], v141 offset:38912
	ds_read_b128 v[230:233], v141 offset:39936
	global_load_lds_dwordx4 v[240:241], off
	v_lshl_add_u64 v[240:241], s[66:67], 0, v[130:131]
	s_mov_b32 m0, s72
	s_nop 0
	global_load_lds_dwordx4 v[240:241], off
	s_waitcnt vmcnt(8)
	s_waitcnt lgkmcnt(0)
	s_barrier
	s_setprio 1
	s_waitcnt lgkmcnt(0)
	v_mfma_f32_16x16x32_bf16 v[126:129], v[142:145], v[192:195], v[126:129]
	v_mfma_f32_16x16x32_bf16 v[118:121], v[168:171], v[192:195], v[118:121]
	v_mfma_f32_16x16x32_bf16 v[110:113], v[142:145], v[200:203], v[110:113]
	v_mfma_f32_16x16x32_bf16 v[102:105], v[168:171], v[200:203], v[102:105]
	v_mfma_f32_16x16x32_bf16 v[94:97], v[142:145], v[208:211], v[94:97]
	v_mfma_f32_16x16x32_bf16 v[86:89], v[168:171], v[208:211], v[86:89]
	v_mfma_f32_16x16x32_bf16 v[78:81], v[142:145], v[226:229], v[78:81]
	v_mfma_f32_16x16x32_bf16 v[70:73], v[168:171], v[226:229], v[70:73]
	v_mfma_f32_16x16x32_bf16 v[126:129], v[164:167], v[196:199], v[126:129]
	v_mfma_f32_16x16x32_bf16 v[118:121], v[172:175], v[196:199], v[118:121]
	v_mfma_f32_16x16x32_bf16 v[110:113], v[164:167], v[204:207], v[110:113]
	v_mfma_f32_16x16x32_bf16 v[102:105], v[172:175], v[204:207], v[102:105]
	v_mfma_f32_16x16x32_bf16 v[94:97], v[164:167], v[222:225], v[94:97]
	v_mfma_f32_16x16x32_bf16 v[86:89], v[172:175], v[222:225], v[86:89]
	v_mfma_f32_16x16x32_bf16 v[78:81], v[164:167], v[230:233], v[78:81]
	v_mfma_f32_16x16x32_bf16 v[70:73], v[172:175], v[230:233], v[70:73]
	v_mfma_f32_16x16x32_bf16 v[122:125], v[176:179], v[192:195], v[122:125]
	v_mfma_f32_16x16x32_bf16 v[114:117], v[184:187], v[192:195], v[114:117]
	v_mfma_f32_16x16x32_bf16 v[106:109], v[176:179], v[200:203], v[106:109]
	v_mfma_f32_16x16x32_bf16 v[98:101], v[184:187], v[200:203], v[98:101]
	v_mfma_f32_16x16x32_bf16 v[90:93], v[176:179], v[208:211], v[90:93]
	v_mfma_f32_16x16x32_bf16 v[82:85], v[184:187], v[208:211], v[82:85]
	v_mfma_f32_16x16x32_bf16 v[74:77], v[176:179], v[226:229], v[74:77]
	v_mfma_f32_16x16x32_bf16 v[66:69], v[184:187], v[226:229], v[66:69]
	v_mfma_f32_16x16x32_bf16 v[122:125], v[180:183], v[196:199], v[122:125]
	v_mfma_f32_16x16x32_bf16 v[114:117], v[188:191], v[196:199], v[114:117]
	v_mfma_f32_16x16x32_bf16 v[106:109], v[180:183], v[204:207], v[106:109]
	v_mfma_f32_16x16x32_bf16 v[98:101], v[188:191], v[204:207], v[98:101]
	v_mfma_f32_16x16x32_bf16 v[90:93], v[180:183], v[222:225], v[90:93]
	v_mfma_f32_16x16x32_bf16 v[82:85], v[188:191], v[222:225], v[82:85]
	v_mfma_f32_16x16x32_bf16 v[74:77], v[180:183], v[230:233], v[74:77]
	v_mfma_f32_16x16x32_bf16 v[66:69], v[188:191], v[230:233], v[66:69]
	s_setprio 0
	s_barrier
; #define PG8_STAGE(bufoff, gbase) do { _Pragma("unroll") for (int _i = 0; _i < 2; ++_i) \
;         __builtin_amdgcn_global_load_lds((const unsigned*)((const char*)(gbase) + voffA[_i]), (LAS unsigned*)(lds + (bufoff) + ldsw + _i * 8192), 16, 0, 0); } while (0)
; #define PG8_LDA(dst, b, h) do { _Pragma("unroll") for (int m = 0; m < 4; ++m) _Pragma("unroll") for (int k = 0; k < 2; ++k) dst[m][k] = *(const LAS bf16x8*)(lds + PG8_SA(b, h) + aoff + m * 2048 + k * 1024); } while (0)
; #define PG8_MMA(ai, bj, At, Bt) do { __builtin_amdgcn_s_setprio(1); _Pragma("unroll") for (int m = 0; m < 4; ++m) _Pragma("unroll") for (int n = 0; n < 2; ++n) _Pragma("unroll") for (int k = 0; k < 2; ++k) \
;         acc[ai][bj][m][n] = __builtin_amdgcn_mfma_f32_16x16x32_bf16(Bt[n][k], At[m][k], acc[ai][bj][m][n], 0, 0, 0); __builtin_amdgcn_s_setprio(0); } while (0)
; #define PG8_WAIT_V(n) asm volatile("s_waitcnt vmcnt(" #n ")" ::: "memory")
; #define PG8_WAIT_L(n) asm volatile("s_waitcnt lgkmcnt(" #n ")" ::: "memory")
; #define PG8_BAR __builtin_amdgcn_s_barrier()
; #define PG8_SCHED __builtin_amdgcn_sched_barrier(0)
; template <class Epi, class Sched>
; __device__ __forceinline__ void gemm_phase(LAS unsigned char* lds, const Gemm g, const Sched& S, const Epi& E) {
;     ...
;             PG8_LDA(At, 1, 1); PG8_STAGE(PG8_SB(1, 0), b3); PG8_STAGE(PG8_SB(1, 1), b3 + hstep); PG8_STAGE(PG8_SA(1, 0), a3);
;             PG8_WAIT_V(8); PG8_WAIT_L(0); PG8_BAR; PG8_MMA(1, 0, At, B0); PG8_MMA(1, 1, At, B1); PG8_BAR; PG8_SCHED;
;         }
	s_add_i32 s66, s99, s57
	v_lshl_add_u64 v[136:137], v[136:137], 0, s[26:27]
	s_mov_b32 m0, s66
	ds_read_b128 v[192:195], v141 offset:49152
	ds_read_b128 v[196:199], v141 offset:50176
	ds_read_b128 v[200:203], v141 offset:51200
	ds_read_b128 v[204:207], v141 offset:52224
	ds_read_b128 v[208:211], v141 offset:53248
	ds_read_b128 v[222:225], v141 offset:54272
	ds_read_b128 v[226:229], v141 offset:55296
	ds_read_b128 v[230:233], v141 offset:56320
	global_load_lds_dwordx4 v[136:137], off
	s_add_i32 m0, s66, 0x2000
	s_add_u32 s64, s64, 0x80080
	v_lshl_add_u64 v[136:137], v[234:235], 0, s[26:27]
	s_addc_u32 s65, s65, 0
	s_add_i32 s66, s91, s57
	global_load_lds_dwordx4 v[136:137], off
	v_lshl_add_u64 v[136:137], s[64:65], 0, v[0:1]
	s_mov_b32 m0, s66
	s_nop 0
	global_load_lds_dwordx4 v[136:137], off
	v_lshl_add_u64 v[136:137], s[64:65], 0, v[130:131]
	s_add_i32 m0, s66, 0x2000
	s_nop 0
	global_load_lds_dwordx4 v[136:137], off
	v_lshl_add_u64 v[136:137], v[236:237], 0, s[26:27]
	s_mov_b32 m0, s73
	s_nop 0
	global_load_lds_dwordx4 v[136:137], off
	v_lshl_add_u64 v[136:137], v[238:239], 0, s[26:27]
	s_mov_b32 m0, s74
	s_nop 0
	global_load_lds_dwordx4 v[136:137], off
	s_waitcnt vmcnt(8)
	s_waitcnt lgkmcnt(0)
	s_barrier
	s_setprio 1
	s_waitcnt lgkmcnt(0)
	v_mfma_f32_16x16x32_bf16 v[62:65], v[142:145], v[192:195], v[62:65]
	v_mfma_f32_16x16x32_bf16 v[54:57], v[168:171], v[192:195], v[54:57]
	v_mfma_f32_16x16x32_bf16 v[46:49], v[142:145], v[200:203], v[46:49]
	v_mfma_f32_16x16x32_bf16 v[38:41], v[168:171], v[200:203], v[38:41]
	v_mfma_f32_16x16x32_bf16 v[30:33], v[142:145], v[208:211], v[30:33]
	v_mfma_f32_16x16x32_bf16 v[22:25], v[168:171], v[208:211], v[22:25]
	v_mfma_f32_16x16x32_bf16 v[14:17], v[142:145], v[226:229], v[14:17]
	v_mfma_f32_16x16x32_bf16 v[6:9], v[168:171], v[226:229], v[6:9]
	v_mfma_f32_16x16x32_bf16 v[62:65], v[164:167], v[196:199], v[62:65]
	v_mfma_f32_16x16x32_bf16 v[54:57], v[172:175], v[196:199], v[54:57]
	v_mfma_f32_16x16x32_bf16 v[46:49], v[164:167], v[204:207], v[46:49]
	v_mfma_f32_16x16x32_bf16 v[38:41], v[172:175], v[204:207], v[38:41]
	v_mfma_f32_16x16x32_bf16 v[30:33], v[164:167], v[222:225], v[30:33]
	v_mfma_f32_16x16x32_bf16 v[22:25], v[172:175], v[222:225], v[22:25]
	v_mfma_f32_16x16x32_bf16 v[14:17], v[164:167], v[230:233], v[14:17]
	v_mfma_f32_16x16x32_bf16 v[6:9], v[172:175], v[230:233], v[6:9]
	v_mfma_f32_16x16x32_bf16 v[58:61], v[176:179], v[192:195], v[58:61]
	v_mfma_f32_16x16x32_bf16 v[50:53], v[184:187], v[192:195], v[50:53]
	v_mfma_f32_16x16x32_bf16 v[42:45], v[176:179], v[200:203], v[42:45]
	v_mfma_f32_16x16x32_bf16 v[34:37], v[184:187], v[200:203], v[34:37]
	v_mfma_f32_16x16x32_bf16 v[26:29], v[176:179], v[208:211], v[26:29]
	v_mfma_f32_16x16x32_bf16 v[18:21], v[184:187], v[208:211], v[18:21]
	v_mfma_f32_16x16x32_bf16 v[10:13], v[176:179], v[226:229], v[10:13]
	v_mfma_f32_16x16x32_bf16 v[2:5], v[184:187], v[226:229], v[2:5]
	v_mfma_f32_16x16x32_bf16 v[58:61], v[180:183], v[196:199], v[58:61]
	v_mfma_f32_16x16x32_bf16 v[50:53], v[188:191], v[196:199], v[50:53]
	v_mfma_f32_16x16x32_bf16 v[42:45], v[180:183], v[204:207], v[42:45]
	v_mfma_f32_16x16x32_bf16 v[34:37], v[188:191], v[204:207], v[34:37]
	v_mfma_f32_16x16x32_bf16 v[26:29], v[180:183], v[222:225], v[26:29]
	v_mfma_f32_16x16x32_bf16 v[18:21], v[188:191], v[222:225], v[18:21]
	v_mfma_f32_16x16x32_bf16 v[10:13], v[180:183], v[230:233], v[10:13]
	v_mfma_f32_16x16x32_bf16 v[2:5], v[188:191], v[230:233], v[2:5]
	s_setprio 0
	s_barrier
	s_add_i32 s90, s90, 2
	s_add_u32 s62, s62, 0x100
	s_addc_u32 s63, s63, 0
	s_add_u32 s88, s88, 0x100
	s_addc_u32 s89, s89, 0
	s_cmp_gt_u32 s90, 29
	s_cbranch_scc0 .LBB0_51
	s_and_b64 vcc, exec, s[20:21]
	s_cbranch_vccz .LBB0_54
	s_barrier

; #define PG8_STAGE(bufoff, gbase) do { _Pragma("unroll") for (int _i = 0; _i < 2; ++_i) \
;         __builtin_amdgcn_global_load_lds((const unsigned*)((const char*)(gbase) + voffA[_i]), (LAS unsigned*)(lds + (bufoff) + ldsw + _i * 8192), 16, 0, 0); } while (0)
; #define PG8_LDA(dst, b, h) do { _Pragma("unroll") for (int m = 0; m < 4; ++m) _Pragma("unroll") for (int k = 0; k < 2; ++k) dst[m][k] = *(const LAS bf16x8*)(lds + PG8_SA(b, h) + aoff + m * 2048 + k * 1024); } while (0)
; #define PG8_LDB(dst, b, h) do { _Pragma("unroll") for (int n = 0; n < 2; ++n) _Pragma("unroll") for (int k = 0; k < 2; ++k) dst[n][k] = *(const LAS bf16x8*)(lds + PG8_SB(b, h) + boff + n * 2048 + k * 1024); } while (0)
; #define PG8_MMA(ai, bj, At, Bt) do { __builtin_amdgcn_s_setprio(1); _Pragma("unroll") for (int m = 0; m < 4; ++m) _Pragma("unroll") for (int n = 0; n < 2; ++n) _Pragma("unroll") for (int k = 0; k < 2; ++k) \
;         acc[ai][bj][m][n] = __builtin_amdgcn_mfma_f32_16x16x32_bf16(Bt[n][k], At[m][k], acc[ai][bj][m][n], 0, 0, 0); __builtin_amdgcn_s_setprio(0); } while (0)
; #define PG8_WAIT_V(n) asm volatile("s_waitcnt vmcnt(" #n ")" ::: "memory")
; #define PG8_WAIT_L(n) asm volatile("s_waitcnt lgkmcnt(" #n ")" ::: "memory")
; #define PG8_BAR __builtin_amdgcn_s_barrier()
; #define PG8_SCHED __builtin_amdgcn_sched_barrier(0)
; template <class Epi, class Sched>
; __device__ __forceinline__ void gemm_phase(LAS unsigned char* lds, const Gemm g, const Sched& S, const Epi& E) {
;     ...
;         for (int t = 0; t < nt; t += 2) {
;             const bool last = (t == nt - 2);
;             const char* a1 = cA + (size_t)(t + 1) * kstep;
;             const char* a2 = last ? nA : cA + (size_t)(t + 2) * kstep; const char* b2 = last ? nB : cB + (size_t)(t + 2) * kstep;
;             const char* a3 = a2 + kstep; const char* b3 = b2 + kstep;
;             PG8_LDB(B0, 0, 0); PG8_LDB(B1, 0, 1); PG8_SCHED; PG8_LDA(At, 0, 0); PG8_STAGE(PG8_SA(1, 1), a1 + hstep);
;             PG8_WAIT_V(8); PG8_WAIT_L(0); PG8_BAR; PG8_MMA(0, 0, At, B0); PG8_MMA(0, 1, At, B1); PG8_BAR; PG8_SCHED;
;             PG8_LDA(At, 0, 1); PG8_STAGE(PG8_SB(0, 0), b2); PG8_STAGE(PG8_SB(0, 1), b2 + hstep); PG8_STAGE(PG8_SA(0, 0), a2);
;             PG8_WAIT_V(8); PG8_WAIT_L(0); PG8_BAR; PG8_MMA(1, 0, At, B0); PG8_MMA(1, 1, At, B1); PG8_BAR; PG8_SCHED;
.LBB0_156:
	s_add_u32 s70, s68, 0xfff80080
	s_addc_u32 s71, s69, -1
	s_add_i32 s92, 0, 0x10000
	s_cmp_eq_u32 s91, 28
	s_cselect_b32 s73, s51, s71
	s_cselect_b32 s72, s67, s70
	v_add_u32_e32 v0, s92, v170
	s_cselect_b32 s71, s49, s90
	s_cselect_b32 s70, s88, s89
	s_add_i32 s94, 0, 0x14000
	ds_read_b128 v[166:169], v0
	ds_read_b128 v[174:177], v0 offset:1024
	ds_read_b128 v[178:181], v0 offset:2048
	ds_read_b128 v[182:185], v0 offset:3072
	v_add_u32_e32 v0, s94, v170
	ds_read_b128 v[186:189], v0
	ds_read_b128 v[190:193], v0 offset:1024
	ds_read_b128 v[194:197], v0 offset:2048
	ds_read_b128 v[198:201], v0 offset:3072
	v_lshl_add_u64 v[210:211], s[68:69], 0, v[138:139]
	s_add_i32 m0, s60, 0xc000
	ds_read_b128 v[202:205], v171
	ds_read_b128 v[206:209], v171 offset:1024
	ds_read_b128 v[222:225], v171 offset:2048
	ds_read_b128 v[226:229], v171 offset:3072
	ds_read_b128 v[230:233], v171 offset:4096
	ds_read_b128 v[234:237], v171 offset:5120
	ds_read_b128 v[238:241], v171 offset:6144
	ds_read_b128 v[242:245], v171 offset:7168
	global_load_lds_dwordx4 v[210:211], off
	v_lshl_add_u64 v[210:211], s[68:69], 0, v[140:141]
	s_add_i32 m0, s60, 0xe000
	s_nop 0
	global_load_lds_dwordx4 v[210:211], off
	s_waitcnt vmcnt(8)
	s_waitcnt lgkmcnt(0)
	s_barrier
	s_setprio 1
	s_waitcnt lgkmcnt(0)
	v_mfma_f32_16x16x32_bf16 v[126:129], v[166:169], v[202:205], v[126:129]
	v_mfma_f32_16x16x32_bf16 v[122:125], v[178:181], v[202:205], v[122:125]
	v_mfma_f32_16x16x32_bf16 v[110:113], v[166:169], v[222:225], v[110:113]
	v_mfma_f32_16x16x32_bf16 v[106:109], v[178:181], v[222:225], v[106:109]
	v_mfma_f32_16x16x32_bf16 v[94:97], v[166:169], v[230:233], v[94:97]
	v_mfma_f32_16x16x32_bf16 v[90:93], v[178:181], v[230:233], v[90:93]
	v_mfma_f32_16x16x32_bf16 v[78:81], v[166:169], v[238:241], v[78:81]
	v_mfma_f32_16x16x32_bf16 v[74:77], v[178:181], v[238:241], v[74:77]
	v_mfma_f32_16x16x32_bf16 v[126:129], v[174:177], v[206:209], v[126:129]
	v_mfma_f32_16x16x32_bf16 v[122:125], v[182:185], v[206:209], v[122:125]
	v_mfma_f32_16x16x32_bf16 v[110:113], v[174:177], v[226:229], v[110:113]
	v_mfma_f32_16x16x32_bf16 v[106:109], v[182:185], v[226:229], v[106:109]
	v_mfma_f32_16x16x32_bf16 v[94:97], v[174:177], v[234:237], v[94:97]
	v_mfma_f32_16x16x32_bf16 v[90:93], v[182:185], v[234:237], v[90:93]
	v_mfma_f32_16x16x32_bf16 v[78:81], v[174:177], v[242:245], v[78:81]
	v_mfma_f32_16x16x32_bf16 v[74:77], v[182:185], v[242:245], v[74:77]
	v_mfma_f32_16x16x32_bf16 v[118:121], v[186:189], v[202:205], v[118:121]
	v_mfma_f32_16x16x32_bf16 v[114:117], v[194:197], v[202:205], v[114:117]
	v_mfma_f32_16x16x32_bf16 v[102:105], v[186:189], v[222:225], v[102:105]
	v_mfma_f32_16x16x32_bf16 v[98:101], v[194:197], v[222:225], v[98:101]
	v_mfma_f32_16x16x32_bf16 v[86:89], v[186:189], v[230:233], v[86:89]
	v_mfma_f32_16x16x32_bf16 v[82:85], v[194:197], v[230:233], v[82:85]
	v_mfma_f32_16x16x32_bf16 v[70:73], v[186:189], v[238:241], v[70:73]
	v_mfma_f32_16x16x32_bf16 v[66:69], v[194:197], v[238:241], v[66:69]
	v_mfma_f32_16x16x32_bf16 v[118:121], v[190:193], v[206:209], v[118:121]
	v_mfma_f32_16x16x32_bf16 v[114:117], v[198:201], v[206:209], v[114:117]
	v_mfma_f32_16x16x32_bf16 v[102:105], v[190:193], v[226:229], v[102:105]
	v_mfma_f32_16x16x32_bf16 v[98:101], v[198:201], v[226:229], v[98:101]
	v_mfma_f32_16x16x32_bf16 v[86:89], v[190:193], v[234:237], v[86:89]
	v_mfma_f32_16x16x32_bf16 v[82:85], v[198:201], v[234:237], v[82:85]
	v_mfma_f32_16x16x32_bf16 v[70:73], v[190:193], v[242:245], v[70:73]
	v_mfma_f32_16x16x32_bf16 v[66:69], v[198:201], v[242:245], v[66:69]
	s_setprio 0
	s_barrier
	s_add_i32 s92, s92, s84
	v_lshl_add_u64 v[210:211], s[70:71], 0, v[132:133]
	s_mov_b32 m0, s92
	ds_read_b128 v[202:205], v171 offset:16384
	ds_read_b128 v[206:209], v171 offset:17408
	ds_read_b128 v[222:225], v171 offset:18432
	ds_read_b128 v[226:229], v171 offset:19456
	ds_read_b128 v[230:233], v171 offset:20480
	ds_read_b128 v[234:237], v171 offset:21504
	ds_read_b128 v[238:241], v171 offset:22528
	ds_read_b128 v[242:245], v171 offset:23552
	global_load_lds_dwordx4 v[210:211], off
	s_add_i32 m0, s92, 0x2000
	s_add_u32 s92, s70, 0x80000
	v_lshl_add_u64 v[216:217], s[70:71], 0, v[130:131]
	s_addc_u32 s93, s71, 0
	s_add_i32 s94, s94, s84
	global_load_lds_dwordx4 v[216:217], off
	v_lshl_add_u64 v[246:247], s[92:93], 0, v[132:133]
	s_mov_b32 m0, s94
	v_lshl_add_u64 v[248:249], s[72:73], 0, v[130:131]
	global_load_lds_dwordx4 v[246:247], off
	v_lshl_add_u64 v[246:247], s[92:93], 0, v[130:131]
	s_add_i32 m0, s94, 0x2000
	s_nop 0
	global_load_lds_dwordx4 v[246:247], off
	v_lshl_add_u64 v[246:247], s[72:73], 0, v[132:133]
	s_mov_b32 m0, s60
	s_nop 0
	global_load_lds_dwordx4 v[246:247], off
	s_mov_b32 m0, s61
	s_nop 0
	global_load_lds_dwordx4 v[248:249], off
	s_waitcnt vmcnt(8)
	s_waitcnt lgkmcnt(0)
	s_barrier
; #define PG8_STAGE(bufoff, gbase) do { _Pragma("unroll") for (int _i = 0; _i < 2; ++_i) \
;         __builtin_amdgcn_global_load_lds((const unsigned*)((const char*)(gbase) + voffA[_i]), (LAS unsigned*)(lds + (bufoff) + ldsw + _i * 8192), 16, 0, 0); } while (0)
; #define PG8_LDA(dst, b, h) do { _Pragma("unroll") for (int m = 0; m < 4; ++m) _Pragma("unroll") for (int k = 0; k < 2; ++k) dst[m][k] = *(const LAS bf16x8*)(lds + PG8_SA(b, h) + aoff + m * 2048 + k * 1024); } while (0)
; #define PG8_LDB(dst, b, h) do { _Pragma("unroll") for (int n = 0; n < 2; ++n) _Pragma("unroll") for (int k = 0; k < 2; ++k) dst[n][k] = *(const LAS bf16x8*)(lds + PG8_SB(b, h) + boff + n * 2048 + k * 1024); } while (0)
; #define PG8_MMA(ai, bj, At, Bt) do { __builtin_amdgcn_s_setprio(1); _Pragma("unroll") for (int m = 0; m < 4; ++m) _Pragma("unroll") for (int n = 0; n < 2; ++n) _Pragma("unroll") for (int k = 0; k < 2; ++k) \
;         acc[ai][bj][m][n] = __builtin_amdgcn_mfma_f32_16x16x32_bf16(Bt[n][k], At[m][k], acc[ai][bj][m][n], 0, 0, 0); __builtin_amdgcn_s_setprio(0); } while (0)
; #define PG8_WAIT_V(n) asm volatile("s_waitcnt vmcnt(" #n ")" ::: "memory")
; #define PG8_WAIT_L(n) asm volatile("s_waitcnt lgkmcnt(" #n ")" ::: "memory")
; #define PG8_BAR __builtin_amdgcn_s_barrier()
; #define PG8_SCHED __builtin_amdgcn_sched_barrier(0)
; template <class Epi, class Sched>
; __device__ __forceinline__ void gemm_phase(LAS unsigned char* lds, const Gemm g, const Sched& S, const Epi& E) {
;     ...
;             PG8_WAIT_V(8); PG8_WAIT_L(0); PG8_BAR; PG8_MMA(1, 0, At, B0); PG8_MMA(1, 1, At, B1); PG8_BAR; PG8_SCHED;
;             PG8_LDB(B0, 1, 0); PG8_LDB(B1, 1, 1); PG8_SCHED; PG8_LDA(At, 1, 0); PG8_STAGE(PG8_SA(0, 1), a2 + hstep);
;             PG8_WAIT_V(8); PG8_WAIT_L(0); PG8_BAR; PG8_MMA(0, 0, At, B0); PG8_MMA(0, 1, At, B1); PG8_BAR; PG8_SCHED;
	s_setprio 1
	s_waitcnt lgkmcnt(0)
	v_mfma_f32_16x16x32_bf16 v[62:65], v[166:169], v[202:205], v[62:65]
	v_mfma_f32_16x16x32_bf16 v[58:61], v[178:181], v[202:205], v[58:61]
	v_mfma_f32_16x16x32_bf16 v[46:49], v[166:169], v[222:225], v[46:49]
	v_mfma_f32_16x16x32_bf16 v[42:45], v[178:181], v[222:225], v[42:45]
	v_mfma_f32_16x16x32_bf16 v[30:33], v[166:169], v[230:233], v[30:33]
	v_mfma_f32_16x16x32_bf16 v[26:29], v[178:181], v[230:233], v[26:29]
	v_mfma_f32_16x16x32_bf16 v[14:17], v[166:169], v[238:241], v[14:17]
	v_mfma_f32_16x16x32_bf16 v[10:13], v[178:181], v[238:241], v[10:13]
	v_mfma_f32_16x16x32_bf16 v[62:65], v[174:177], v[206:209], v[62:65]
	v_mfma_f32_16x16x32_bf16 v[58:61], v[182:185], v[206:209], v[58:61]
	v_mfma_f32_16x16x32_bf16 v[46:49], v[174:177], v[226:229], v[46:49]
	v_mfma_f32_16x16x32_bf16 v[42:45], v[182:185], v[226:229], v[42:45]
	v_mfma_f32_16x16x32_bf16 v[30:33], v[174:177], v[234:237], v[30:33]
	v_mfma_f32_16x16x32_bf16 v[26:29], v[182:185], v[234:237], v[26:29]
	v_mfma_f32_16x16x32_bf16 v[14:17], v[174:177], v[242:245], v[14:17]
	v_mfma_f32_16x16x32_bf16 v[10:13], v[182:185], v[242:245], v[10:13]
	v_mfma_f32_16x16x32_bf16 v[54:57], v[186:189], v[202:205], v[54:57]
	v_mfma_f32_16x16x32_bf16 v[50:53], v[194:197], v[202:205], v[50:53]
	v_mfma_f32_16x16x32_bf16 v[38:41], v[186:189], v[222:225], v[38:41]
	v_mfma_f32_16x16x32_bf16 v[34:37], v[194:197], v[222:225], v[34:37]
	v_mfma_f32_16x16x32_bf16 v[22:25], v[186:189], v[230:233], v[22:25]
	v_mfma_f32_16x16x32_bf16 v[18:21], v[194:197], v[230:233], v[18:21]
	v_mfma_f32_16x16x32_bf16 v[6:9], v[186:189], v[238:241], v[6:9]
	v_mfma_f32_16x16x32_bf16 v[2:5], v[194:197], v[238:241], v[2:5]
	v_mfma_f32_16x16x32_bf16 v[54:57], v[190:193], v[206:209], v[54:57]
	v_mfma_f32_16x16x32_bf16 v[50:53], v[198:201], v[206:209], v[50:53]
	v_mfma_f32_16x16x32_bf16 v[38:41], v[190:193], v[226:229], v[38:41]
	v_mfma_f32_16x16x32_bf16 v[34:37], v[198:201], v[226:229], v[34:37]
	v_mfma_f32_16x16x32_bf16 v[22:25], v[190:193], v[234:237], v[22:25]
	v_mfma_f32_16x16x32_bf16 v[18:21], v[198:201], v[234:237], v[18:21]
	v_mfma_f32_16x16x32_bf16 v[6:9], v[190:193], v[242:245], v[6:9]
	v_mfma_f32_16x16x32_bf16 v[2:5], v[198:201], v[242:245], v[2:5]
	s_setprio 0
	s_barrier
	v_add_u32_e32 v0, s99, v170
	s_add_i32 s92, 0, 0x1c000
	ds_read_b128 v[166:169], v0
	ds_read_b128 v[174:177], v0 offset:1024
	ds_read_b128 v[178:181], v0 offset:2048
	ds_read_b128 v[182:185], v0 offset:3072
	v_add_u32_e32 v0, s92, v170
	ds_read_b128 v[186:189], v0
	ds_read_b128 v[190:193], v0 offset:1024
	ds_read_b128 v[194:197], v0 offset:2048
	ds_read_b128 v[198:201], v0 offset:3072
	s_add_u32 s72, s72, 0x80000
	s_addc_u32 s73, s73, 0
	s_mov_b32 m0, s44
	v_lshl_add_u64 v[250:251], s[72:73], 0, v[132:133]
	ds_read_b128 v[202:205], v171 offset:32768
	ds_read_b128 v[206:209], v171 offset:33792
	ds_read_b128 v[222:225], v171 offset:34816
	ds_read_b128 v[226:229], v171 offset:35840
	ds_read_b128 v[230:233], v171 offset:36864
	ds_read_b128 v[234:237], v171 offset:37888
	ds_read_b128 v[238:241], v171 offset:38912
	ds_read_b128 v[242:245], v171 offset:39936
	global_load_lds_dwordx4 v[250:251], off
	v_lshl_add_u64 v[250:251], s[72:73], 0, v[130:131]
	s_mov_b32 m0, s45
	s_nop 0
	global_load_lds_dwordx4 v[250:251], off
	s_waitcnt vmcnt(8)
	s_waitcnt lgkmcnt(0)
	s_barrier
	s_setprio 1
	s_waitcnt lgkmcnt(0)
	v_mfma_f32_16x16x32_bf16 v[126:129], v[166:169], v[202:205], v[126:129]
	v_mfma_f32_16x16x32_bf16 v[122:125], v[178:181], v[202:205], v[122:125]
	v_mfma_f32_16x16x32_bf16 v[110:113], v[166:169], v[222:225], v[110:113]
	v_mfma_f32_16x16x32_bf16 v[106:109], v[178:181], v[222:225], v[106:109]
	v_mfma_f32_16x16x32_bf16 v[94:97], v[166:169], v[230:233], v[94:97]
	v_mfma_f32_16x16x32_bf16 v[90:93], v[178:181], v[230:233], v[90:93]
	v_mfma_f32_16x16x32_bf16 v[78:81], v[166:169], v[238:241], v[78:81]
	v_mfma_f32_16x16x32_bf16 v[74:77], v[178:181], v[238:241], v[74:77]
	v_mfma_f32_16x16x32_bf16 v[126:129], v[174:177], v[206:209], v[126:129]
	v_mfma_f32_16x16x32_bf16 v[122:125], v[182:185], v[206:209], v[122:125]
	v_mfma_f32_16x16x32_bf16 v[110:113], v[174:177], v[226:229], v[110:113]
	v_mfma_f32_16x16x32_bf16 v[106:109], v[182:185], v[226:229], v[106:109]
	v_mfma_f32_16x16x32_bf16 v[94:97], v[174:177], v[234:237], v[94:97]
	v_mfma_f32_16x16x32_bf16 v[90:93], v[182:185], v[234:237], v[90:93]
	v_mfma_f32_16x16x32_bf16 v[78:81], v[174:177], v[242:245], v[78:81]
	v_mfma_f32_16x16x32_bf16 v[74:77], v[182:185], v[242:245], v[74:77]
	v_mfma_f32_16x16x32_bf16 v[118:121], v[186:189], v[202:205], v[118:121]
	v_mfma_f32_16x16x32_bf16 v[114:117], v[194:197], v[202:205], v[114:117]
	v_mfma_f32_16x16x32_bf16 v[102:105], v[186:189], v[222:225], v[102:105]
	v_mfma_f32_16x16x32_bf16 v[98:101], v[194:197], v[222:225], v[98:101]
	v_mfma_f32_16x16x32_bf16 v[86:89], v[186:189], v[230:233], v[86:89]
	v_mfma_f32_16x16x32_bf16 v[82:85], v[194:197], v[230:233], v[82:85]
	v_mfma_f32_16x16x32_bf16 v[70:73], v[186:189], v[238:241], v[70:73]
	v_mfma_f32_16x16x32_bf16 v[66:69], v[194:197], v[238:241], v[66:69]
	v_mfma_f32_16x16x32_bf16 v[118:121], v[190:193], v[206:209], v[118:121]
	v_mfma_f32_16x16x32_bf16 v[114:117], v[198:201], v[206:209], v[114:117]
	v_mfma_f32_16x16x32_bf16 v[102:105], v[190:193], v[226:229], v[102:105]
	v_mfma_f32_16x16x32_bf16 v[98:101], v[198:201], v[226:229], v[98:101]
	v_mfma_f32_16x16x32_bf16 v[86:89], v[190:193], v[234:237], v[86:89]
	v_mfma_f32_16x16x32_bf16 v[82:85], v[198:201], v[234:237], v[82:85]
	v_mfma_f32_16x16x32_bf16 v[70:73], v[190:193], v[242:245], v[70:73]
	v_mfma_f32_16x16x32_bf16 v[66:69], v[198:201], v[242:245], v[66:69]
	s_setprio 0
	s_barrier
; #define PG8_STAGE(bufoff, gbase) do { _Pragma("unroll") for (int _i = 0; _i < 2; ++_i) \
;         __builtin_amdgcn_global_load_lds((const unsigned*)((const char*)(gbase) + voffA[_i]), (LAS unsigned*)(lds + (bufoff) + ldsw + _i * 8192), 16, 0, 0); } while (0)
; #define PG8_LDA(dst, b, h) do { _Pragma("unroll") for (int m = 0; m < 4; ++m) _Pragma("unroll") for (int k = 0; k < 2; ++k) dst[m][k] = *(const LAS bf16x8*)(lds + PG8_SA(b, h) + aoff + m * 2048 + k * 1024); } while (0)
; #define PG8_MMA(ai, bj, At, Bt) do { __builtin_amdgcn_s_setprio(1); _Pragma("unroll") for (int m = 0; m < 4; ++m) _Pragma("unroll") for (int n = 0; n < 2; ++n) _Pragma("unroll") for (int k = 0; k < 2; ++k) \
;         acc[ai][bj][m][n] = __builtin_amdgcn_mfma_f32_16x16x32_bf16(Bt[n][k], At[m][k], acc[ai][bj][m][n], 0, 0, 0); __builtin_amdgcn_s_setprio(0); } while (0)
; #define PG8_WAIT_V(n) asm volatile("s_waitcnt vmcnt(" #n ")" ::: "memory")
; #define PG8_WAIT_L(n) asm volatile("s_waitcnt lgkmcnt(" #n ")" ::: "memory")
; #define PG8_BAR __builtin_amdgcn_s_barrier()
; #define PG8_SCHED __builtin_amdgcn_sched_barrier(0)
; template <class Epi, class Sched>
; __device__ __forceinline__ void gemm_phase(LAS unsigned char* lds, const Gemm g, const Sched& S, const Epi& E) {
;     ...
;             PG8_LDA(At, 1, 1); PG8_STAGE(PG8_SB(1, 0), b3); PG8_STAGE(PG8_SB(1, 1), b3 + hstep); PG8_STAGE(PG8_SA(1, 0), a3);
;             PG8_WAIT_V(8); PG8_WAIT_L(0); PG8_BAR; PG8_MMA(1, 0, At, B0); PG8_MMA(1, 1, At, B1); PG8_BAR; PG8_SCHED;
;         }
	s_add_i32 s72, s99, s84
	v_lshl_add_u64 v[210:211], v[210:211], 0, s[26:27]
	s_mov_b32 m0, s72
	ds_read_b128 v[202:205], v171 offset:49152
	ds_read_b128 v[206:209], v171 offset:50176
	ds_read_b128 v[222:225], v171 offset:51200
	ds_read_b128 v[226:229], v171 offset:52224
	ds_read_b128 v[230:233], v171 offset:53248
	ds_read_b128 v[234:237], v171 offset:54272
	ds_read_b128 v[238:241], v171 offset:55296
	ds_read_b128 v[242:245], v171 offset:56320
	global_load_lds_dwordx4 v[210:211], off
	s_add_i32 m0, s72, 0x2000
	s_add_u32 s70, s70, 0x80080
	v_lshl_add_u64 v[210:211], v[216:217], 0, s[26:27]
	s_addc_u32 s71, s71, 0
	s_add_i32 s72, s92, s84
	global_load_lds_dwordx4 v[210:211], off
	v_lshl_add_u64 v[210:211], s[70:71], 0, v[132:133]
	s_mov_b32 m0, s72
	s_nop 0
	global_load_lds_dwordx4 v[210:211], off
	v_lshl_add_u64 v[210:211], s[70:71], 0, v[130:131]
	s_add_i32 m0, s72, 0x2000
	s_nop 0
	global_load_lds_dwordx4 v[210:211], off
	v_lshl_add_u64 v[210:211], v[246:247], 0, s[26:27]
	s_mov_b32 m0, s38
	s_nop 0
	global_load_lds_dwordx4 v[210:211], off
	v_lshl_add_u64 v[210:211], v[248:249], 0, s[26:27]
	s_mov_b32 m0, s39
	s_nop 0
	global_load_lds_dwordx4 v[210:211], off
	s_waitcnt vmcnt(8)
	s_waitcnt lgkmcnt(0)
	s_barrier
	s_setprio 1
	s_waitcnt lgkmcnt(0)
	v_mfma_f32_16x16x32_bf16 v[62:65], v[166:169], v[202:205], v[62:65]
	v_mfma_f32_16x16x32_bf16 v[58:61], v[178:181], v[202:205], v[58:61]
	v_mfma_f32_16x16x32_bf16 v[46:49], v[166:169], v[222:225], v[46:49]
	v_mfma_f32_16x16x32_bf16 v[42:45], v[178:181], v[222:225], v[42:45]
	v_mfma_f32_16x16x32_bf16 v[30:33], v[166:169], v[230:233], v[30:33]
	v_mfma_f32_16x16x32_bf16 v[26:29], v[178:181], v[230:233], v[26:29]
	v_mfma_f32_16x16x32_bf16 v[14:17], v[166:169], v[238:241], v[14:17]
	v_mfma_f32_16x16x32_bf16 v[10:13], v[178:181], v[238:241], v[10:13]
	v_mfma_f32_16x16x32_bf16 v[62:65], v[174:177], v[206:209], v[62:65]
	v_mfma_f32_16x16x32_bf16 v[58:61], v[182:185], v[206:209], v[58:61]
	v_mfma_f32_16x16x32_bf16 v[46:49], v[174:177], v[226:229], v[46:49]
	v_mfma_f32_16x16x32_bf16 v[42:45], v[182:185], v[226:229], v[42:45]
	v_mfma_f32_16x16x32_bf16 v[30:33], v[174:177], v[234:237], v[30:33]
	v_mfma_f32_16x16x32_bf16 v[26:29], v[182:185], v[234:237], v[26:29]
	v_mfma_f32_16x16x32_bf16 v[14:17], v[174:177], v[242:245], v[14:17]
	v_mfma_f32_16x16x32_bf16 v[10:13], v[182:185], v[242:245], v[10:13]
	v_mfma_f32_16x16x32_bf16 v[54:57], v[186:189], v[202:205], v[54:57]
	v_mfma_f32_16x16x32_bf16 v[50:53], v[194:197], v[202:205], v[50:53]
	v_mfma_f32_16x16x32_bf16 v[38:41], v[186:189], v[222:225], v[38:41]
	v_mfma_f32_16x16x32_bf16 v[34:37], v[194:197], v[222:225], v[34:37]
	v_mfma_f32_16x16x32_bf16 v[22:25], v[186:189], v[230:233], v[22:25]
	v_mfma_f32_16x16x32_bf16 v[18:21], v[194:197], v[230:233], v[18:21]
	v_mfma_f32_16x16x32_bf16 v[6:9], v[186:189], v[238:241], v[6:9]
	v_mfma_f32_16x16x32_bf16 v[2:5], v[194:197], v[238:241], v[2:5]
	v_mfma_f32_16x16x32_bf16 v[54:57], v[190:193], v[206:209], v[54:57]
	v_mfma_f32_16x16x32_bf16 v[50:53], v[198:201], v[206:209], v[50:53]
	v_mfma_f32_16x16x32_bf16 v[38:41], v[190:193], v[226:229], v[38:41]
	v_mfma_f32_16x16x32_bf16 v[34:37], v[198:201], v[226:229], v[34:37]
	v_mfma_f32_16x16x32_bf16 v[22:25], v[190:193], v[234:237], v[22:25]
	v_mfma_f32_16x16x32_bf16 v[18:21], v[198:201], v[234:237], v[18:21]
	v_mfma_f32_16x16x32_bf16 v[6:9], v[190:193], v[242:245], v[6:9]
	v_mfma_f32_16x16x32_bf16 v[2:5], v[198:201], v[242:245], v[2:5]
	s_setprio 0
	s_barrier
	s_add_i32 s91, s91, 2
	s_add_u32 s68, s68, 0x100
	s_addc_u32 s69, s69, 0
	s_add_u32 s89, s89, 0x100
	s_addc_u32 s90, s90, 0
	s_cmp_gt_u32 s91, 29
	s_cbranch_scc0 .LBB0_156
	s_and_b64 vcc, exec, s[46:47]
	s_cbranch_vccz .LBB0_159
	s_barrier

; #define PG8_STAGE(bufoff, gbase) do { _Pragma("unroll") for (int _i = 0; _i < 2; ++_i) \
;         __builtin_amdgcn_global_load_lds((const unsigned*)((const char*)(gbase) + voffA[_i]), (LAS unsigned*)(lds + (bufoff) + ldsw + _i * 8192), 16, 0, 0); } while (0)
; #define PG8_LDA(dst, b, h) do { _Pragma("unroll") for (int m = 0; m < 4; ++m) _Pragma("unroll") for (int k = 0; k < 2; ++k) dst[m][k] = *(const LAS bf16x8*)(lds + PG8_SA(b, h) + aoff + m * 2048 + k * 1024); } while (0)
; #define PG8_LDB(dst, b, h) do { _Pragma("unroll") for (int n = 0; n < 2; ++n) _Pragma("unroll") for (int k = 0; k < 2; ++k) dst[n][k] = *(const LAS bf16x8*)(lds + PG8_SB(b, h) + boff + n * 2048 + k * 1024); } while (0)
; #define PG8_MMA(ai, bj, At, Bt) do { __builtin_amdgcn_s_setprio(1); _Pragma("unroll") for (int m = 0; m < 4; ++m) _Pragma("unroll") for (int n = 0; n < 2; ++n) _Pragma("unroll") for (int k = 0; k < 2; ++k) \
;         acc[ai][bj][m][n] = __builtin_amdgcn_mfma_f32_16x16x32_bf16(Bt[n][k], At[m][k], acc[ai][bj][m][n], 0, 0, 0); __builtin_amdgcn_s_setprio(0); } while (0)
; #define PG8_WAIT_V(n) asm volatile("s_waitcnt vmcnt(" #n ")" ::: "memory")
; #define PG8_WAIT_L(n) asm volatile("s_waitcnt lgkmcnt(" #n ")" ::: "memory")
; #define PG8_BAR __builtin_amdgcn_s_barrier()
; #define PG8_SCHED __builtin_amdgcn_sched_barrier(0)
; template <class Epi, class Sched>
; __device__ __forceinline__ void gemm_phase(LAS unsigned char* lds, const Gemm g, const Sched& S, const Epi& E) {
;     ...
;         for (int t = 0; t < nt; t += 2) {
;             const bool last = (t == nt - 2);
;             const char* a1 = cA + (size_t)(t + 1) * kstep;
;             const char* a2 = last ? nA : cA + (size_t)(t + 2) * kstep; const char* b2 = last ? nB : cB + (size_t)(t + 2) * kstep;
;             const char* a3 = a2 + kstep; const char* b3 = b2 + kstep;
;             PG8_LDB(B0, 0, 0); PG8_LDB(B1, 0, 1); PG8_SCHED; PG8_LDA(At, 0, 0); PG8_STAGE(PG8_SA(1, 1), a1 + hstep);
;             PG8_WAIT_V(8); PG8_WAIT_L(0); PG8_BAR; PG8_MMA(0, 0, At, B0); PG8_MMA(0, 1, At, B1); PG8_BAR; PG8_SCHED;
;             PG8_LDA(At, 0, 1); PG8_STAGE(PG8_SB(0, 0), b2); PG8_STAGE(PG8_SB(0, 1), b2 + hstep); PG8_STAGE(PG8_SA(0, 0), a2);
;             PG8_WAIT_V(8); PG8_WAIT_L(0); PG8_BAR; PG8_MMA(1, 0, At, B0); PG8_MMA(1, 1, At, B1); PG8_BAR; PG8_SCHED;
.LBB0_292:
	s_add_i32 s93, s72, 2
	s_add_u32 s94, s46, 0x80
	s_addc_u32 s73, s47, 0
	s_add_i32 vcc_lo, 0, 0x10000
	s_cmp_eq_u32 s90, s72
	s_cselect_b32 s72, s68, s94
	s_cselect_b32 s94, 0, s70
	s_cselect_b32 s73, s69, s73
	s_cselect_b32 s95, 0, s71
	s_add_u32 s94, s14, s94
	s_addc_u32 s95, s15, s95
	s_add_i32 vcc_hi, 0, 0x14000
	v_add_u32_e32 v142, vcc_lo, v223
	v_add_u32_e32 v192, vcc_hi, v223
	ds_read_b128 v[130:133], v142
	ds_read_b128 v[134:137], v142 offset:1024
	ds_read_b128 v[138:141], v142 offset:2048
	ds_read_b128 v[142:145], v142 offset:3072
	ds_read_b128 v[180:183], v192
	ds_read_b128 v[184:187], v192 offset:1024
	ds_read_b128 v[188:191], v192 offset:2048
	ds_read_b128 v[192:195], v192 offset:3072
	v_lshl_add_u64 v[242:243], s[46:47], 0, v[176:177]
	s_add_i32 m0, s41, 0xc000
	ds_read_b128 v[196:199], v224
	ds_read_b128 v[200:203], v224 offset:1024
	ds_read_b128 v[204:207], v224 offset:2048
	ds_read_b128 v[208:211], v224 offset:3072
	ds_read_b128 v[226:229], v224 offset:4096
	ds_read_b128 v[230:233], v224 offset:5120
	ds_read_b128 v[234:237], v224 offset:6144
	ds_read_b128 v[238:241], v224 offset:7168
	global_load_lds_dwordx4 v[242:243], off
	v_lshl_add_u64 v[242:243], s[46:47], 0, v[178:179]
	s_add_i32 m0, s41, 0xe000
	s_nop 0
	global_load_lds_dwordx4 v[242:243], off
	s_waitcnt vmcnt(8)
	s_waitcnt lgkmcnt(0)
	s_barrier
	s_setprio 1
	s_waitcnt lgkmcnt(0)
	v_mfma_f32_16x16x32_bf16 v[2:5], v[130:133], v[196:199], v[2:5]
	v_mfma_f32_16x16x32_bf16 v[6:9], v[138:141], v[196:199], v[6:9]
	v_mfma_f32_16x16x32_bf16 v[18:21], v[130:133], v[204:207], v[18:21]
	v_mfma_f32_16x16x32_bf16 v[26:29], v[138:141], v[204:207], v[26:29]
	v_mfma_f32_16x16x32_bf16 v[34:37], v[130:133], v[226:229], v[34:37]
	v_mfma_f32_16x16x32_bf16 v[42:45], v[138:141], v[226:229], v[42:45]
	v_mfma_f32_16x16x32_bf16 v[50:53], v[130:133], v[234:237], v[50:53]
	v_mfma_f32_16x16x32_bf16 v[58:61], v[138:141], v[234:237], v[58:61]
	v_mfma_f32_16x16x32_bf16 v[2:5], v[134:137], v[200:203], v[2:5]
	v_mfma_f32_16x16x32_bf16 v[6:9], v[142:145], v[200:203], v[6:9]
	v_mfma_f32_16x16x32_bf16 v[18:21], v[134:137], v[208:211], v[18:21]
	v_mfma_f32_16x16x32_bf16 v[26:29], v[142:145], v[208:211], v[26:29]
	v_mfma_f32_16x16x32_bf16 v[34:37], v[134:137], v[230:233], v[34:37]
	v_mfma_f32_16x16x32_bf16 v[42:45], v[142:145], v[230:233], v[42:45]
	v_mfma_f32_16x16x32_bf16 v[50:53], v[134:137], v[238:241], v[50:53]
	v_mfma_f32_16x16x32_bf16 v[58:61], v[142:145], v[238:241], v[58:61]
	v_mfma_f32_16x16x32_bf16 v[10:13], v[180:183], v[196:199], v[10:13]
	v_mfma_f32_16x16x32_bf16 v[14:17], v[188:191], v[196:199], v[14:17]
	v_mfma_f32_16x16x32_bf16 v[22:25], v[180:183], v[204:207], v[22:25]
	v_mfma_f32_16x16x32_bf16 v[30:33], v[188:191], v[204:207], v[30:33]
	v_mfma_f32_16x16x32_bf16 v[38:41], v[180:183], v[226:229], v[38:41]
	v_mfma_f32_16x16x32_bf16 v[46:49], v[188:191], v[226:229], v[46:49]
	v_mfma_f32_16x16x32_bf16 v[54:57], v[180:183], v[234:237], v[54:57]
	v_mfma_f32_16x16x32_bf16 v[62:65], v[188:191], v[234:237], v[62:65]
	v_mfma_f32_16x16x32_bf16 v[10:13], v[184:187], v[200:203], v[10:13]
	v_mfma_f32_16x16x32_bf16 v[14:17], v[192:195], v[200:203], v[14:17]
	v_mfma_f32_16x16x32_bf16 v[22:25], v[184:187], v[208:211], v[22:25]
	v_mfma_f32_16x16x32_bf16 v[30:33], v[192:195], v[208:211], v[30:33]
	v_mfma_f32_16x16x32_bf16 v[38:41], v[184:187], v[230:233], v[38:41]
	v_mfma_f32_16x16x32_bf16 v[46:49], v[192:195], v[230:233], v[46:49]
	v_mfma_f32_16x16x32_bf16 v[54:57], v[184:187], v[238:241], v[54:57]
	v_mfma_f32_16x16x32_bf16 v[62:65], v[192:195], v[238:241], v[62:65]
	s_setprio 0
	s_barrier
	s_add_i32 vcc_lo, vcc_lo, s56
	v_lshl_add_u64 v[242:243], s[94:95], 0, v[0:1]
	s_mov_b32 m0, vcc_lo
	ds_read_b128 v[196:199], v224 offset:16384
	ds_read_b128 v[200:203], v224 offset:17408
	ds_read_b128 v[204:207], v224 offset:18432
	ds_read_b128 v[208:211], v224 offset:19456
	ds_read_b128 v[226:229], v224 offset:20480
	ds_read_b128 v[230:233], v224 offset:21504
	ds_read_b128 v[234:237], v224 offset:22528
	ds_read_b128 v[238:241], v224 offset:23552
	global_load_lds_dwordx4 v[242:243], off
	s_add_i32 m0, vcc_lo, 0x2000
	v_lshl_add_u64 v[244:245], s[94:95], 0, v[164:165]
	s_add_u32 s94, s94, s36
	s_addc_u32 s95, s95, 0
	s_add_i32 vcc_lo, vcc_hi, s56
	global_load_lds_dwordx4 v[244:245], off
	v_lshl_add_u64 v[246:247], s[94:95], 0, v[0:1]
	s_mov_b32 m0, vcc_lo
	v_lshl_add_u64 v[248:249], s[94:95], 0, v[164:165]
	global_load_lds_dwordx4 v[246:247], off
	s_add_i32 m0, vcc_lo, 0x2000
	v_lshl_add_u64 v[250:251], s[72:73], 0, v[0:1]
	global_load_lds_dwordx4 v[248:249], off
	s_mov_b32 m0, s41
	v_lshl_add_u64 v[252:253], s[72:73], 0, v[164:165]
	global_load_lds_dwordx4 v[250:251], off
	s_mov_b32 m0, s52
	s_nop 0
	global_load_lds_dwordx4 v[252:253], off
	s_waitcnt vmcnt(8)
	s_waitcnt lgkmcnt(0)
	s_barrier
; #define PG8_STAGE(bufoff, gbase) do { _Pragma("unroll") for (int _i = 0; _i < 2; ++_i) \
;         __builtin_amdgcn_global_load_lds((const unsigned*)((const char*)(gbase) + voffA[_i]), (LAS unsigned*)(lds + (bufoff) + ldsw + _i * 8192), 16, 0, 0); } while (0)
; #define PG8_LDA(dst, b, h) do { _Pragma("unroll") for (int m = 0; m < 4; ++m) _Pragma("unroll") for (int k = 0; k < 2; ++k) dst[m][k] = *(const LAS bf16x8*)(lds + PG8_SA(b, h) + aoff + m * 2048 + k * 1024); } while (0)
; #define PG8_LDB(dst, b, h) do { _Pragma("unroll") for (int n = 0; n < 2; ++n) _Pragma("unroll") for (int k = 0; k < 2; ++k) dst[n][k] = *(const LAS bf16x8*)(lds + PG8_SB(b, h) + boff + n * 2048 + k * 1024); } while (0)
; #define PG8_MMA(ai, bj, At, Bt) do { __builtin_amdgcn_s_setprio(1); _Pragma("unroll") for (int m = 0; m < 4; ++m) _Pragma("unroll") for (int n = 0; n < 2; ++n) _Pragma("unroll") for (int k = 0; k < 2; ++k) \
;         acc[ai][bj][m][n] = __builtin_amdgcn_mfma_f32_16x16x32_bf16(Bt[n][k], At[m][k], acc[ai][bj][m][n], 0, 0, 0); __builtin_amdgcn_s_setprio(0); } while (0)
; #define PG8_WAIT_V(n) asm volatile("s_waitcnt vmcnt(" #n ")" ::: "memory")
; #define PG8_WAIT_L(n) asm volatile("s_waitcnt lgkmcnt(" #n ")" ::: "memory")
; #define PG8_BAR __builtin_amdgcn_s_barrier()
; #define PG8_SCHED __builtin_amdgcn_sched_barrier(0)
; template <class Epi, class Sched>
; __device__ __forceinline__ void gemm_phase(LAS unsigned char* lds, const Gemm g, const Sched& S, const Epi& E) {
;     ...
;             PG8_WAIT_V(8); PG8_WAIT_L(0); PG8_BAR; PG8_MMA(1, 0, At, B0); PG8_MMA(1, 1, At, B1); PG8_BAR; PG8_SCHED;
;             PG8_LDB(B0, 1, 0); PG8_LDB(B1, 1, 1); PG8_SCHED; PG8_LDA(At, 1, 0); PG8_STAGE(PG8_SA(0, 1), a2 + hstep);
;             PG8_WAIT_V(8); PG8_WAIT_L(0); PG8_BAR; PG8_MMA(0, 0, At, B0); PG8_MMA(0, 1, At, B1); PG8_BAR; PG8_SCHED;
	s_setprio 1
	s_waitcnt lgkmcnt(0)
	v_mfma_f32_16x16x32_bf16 v[66:69], v[130:133], v[196:199], v[66:69]
	v_mfma_f32_16x16x32_bf16 v[74:77], v[138:141], v[196:199], v[74:77]
	v_mfma_f32_16x16x32_bf16 v[82:85], v[130:133], v[204:207], v[82:85]
	v_mfma_f32_16x16x32_bf16 v[90:93], v[138:141], v[204:207], v[90:93]
	v_mfma_f32_16x16x32_bf16 v[98:101], v[130:133], v[226:229], v[98:101]
	v_mfma_f32_16x16x32_bf16 v[106:109], v[138:141], v[226:229], v[106:109]
	v_mfma_f32_16x16x32_bf16 v[114:117], v[130:133], v[234:237], v[114:117]
	v_mfma_f32_16x16x32_bf16 v[122:125], v[138:141], v[234:237], v[122:125]
	v_mfma_f32_16x16x32_bf16 v[66:69], v[134:137], v[200:203], v[66:69]
	v_mfma_f32_16x16x32_bf16 v[74:77], v[142:145], v[200:203], v[74:77]
	v_mfma_f32_16x16x32_bf16 v[82:85], v[134:137], v[208:211], v[82:85]
	v_mfma_f32_16x16x32_bf16 v[90:93], v[142:145], v[208:211], v[90:93]
	v_mfma_f32_16x16x32_bf16 v[98:101], v[134:137], v[230:233], v[98:101]
	v_mfma_f32_16x16x32_bf16 v[106:109], v[142:145], v[230:233], v[106:109]
	v_mfma_f32_16x16x32_bf16 v[114:117], v[134:137], v[238:241], v[114:117]
	v_mfma_f32_16x16x32_bf16 v[122:125], v[142:145], v[238:241], v[122:125]
	v_mfma_f32_16x16x32_bf16 v[70:73], v[180:183], v[196:199], v[70:73]
	v_mfma_f32_16x16x32_bf16 v[78:81], v[188:191], v[196:199], v[78:81]
	v_mfma_f32_16x16x32_bf16 v[86:89], v[180:183], v[204:207], v[86:89]
	v_mfma_f32_16x16x32_bf16 v[94:97], v[188:191], v[204:207], v[94:97]
	v_mfma_f32_16x16x32_bf16 v[102:105], v[180:183], v[226:229], v[102:105]
	v_mfma_f32_16x16x32_bf16 v[110:113], v[188:191], v[226:229], v[110:113]
	v_mfma_f32_16x16x32_bf16 v[118:121], v[180:183], v[234:237], v[118:121]
	v_mfma_f32_16x16x32_bf16 v[126:129], v[188:191], v[234:237], v[126:129]
	v_mfma_f32_16x16x32_bf16 v[70:73], v[184:187], v[200:203], v[70:73]
	v_mfma_f32_16x16x32_bf16 v[78:81], v[192:195], v[200:203], v[78:81]
	v_mfma_f32_16x16x32_bf16 v[86:89], v[184:187], v[208:211], v[86:89]
	v_mfma_f32_16x16x32_bf16 v[94:97], v[192:195], v[208:211], v[94:97]
	v_mfma_f32_16x16x32_bf16 v[102:105], v[184:187], v[230:233], v[102:105]
	v_mfma_f32_16x16x32_bf16 v[110:113], v[192:195], v[230:233], v[110:113]
	v_mfma_f32_16x16x32_bf16 v[118:121], v[184:187], v[238:241], v[118:121]
	v_mfma_f32_16x16x32_bf16 v[126:129], v[192:195], v[238:241], v[126:129]
	s_setprio 0
	s_barrier
	s_add_i32 s94, 0, 0x1c000
	v_add_u32_e32 v142, s99, v223
	v_add_u32_e32 v192, s94, v223
	ds_read_b128 v[130:133], v142
	ds_read_b128 v[134:137], v142 offset:1024
	ds_read_b128 v[138:141], v142 offset:2048
	ds_read_b128 v[142:145], v142 offset:3072
	ds_read_b128 v[180:183], v192
	ds_read_b128 v[184:187], v192 offset:1024
	ds_read_b128 v[188:191], v192 offset:2048
	ds_read_b128 v[192:195], v192 offset:3072
	s_add_u32 s72, s72, s36
	s_addc_u32 s73, s73, 0
	s_mov_b32 m0, s33
	v_lshl_add_u64 v[216:217], s[72:73], 0, v[0:1]
	ds_read_b128 v[196:199], v224 offset:32768
	ds_read_b128 v[200:203], v224 offset:33792
	ds_read_b128 v[204:207], v224 offset:34816
	ds_read_b128 v[208:211], v224 offset:35840
	ds_read_b128 v[226:229], v224 offset:36864
	ds_read_b128 v[230:233], v224 offset:37888
	ds_read_b128 v[234:237], v224 offset:38912
	ds_read_b128 v[238:241], v224 offset:39936
	global_load_lds_dwordx4 v[216:217], off
	v_lshl_add_u64 v[216:217], s[72:73], 0, v[164:165]
	s_mov_b32 m0, s0
	s_nop 0
	global_load_lds_dwordx4 v[216:217], off
	s_waitcnt vmcnt(8)
	s_waitcnt lgkmcnt(0)
	s_barrier
	s_setprio 1
	s_waitcnt lgkmcnt(0)
	v_mfma_f32_16x16x32_bf16 v[2:5], v[130:133], v[196:199], v[2:5]
	v_mfma_f32_16x16x32_bf16 v[6:9], v[138:141], v[196:199], v[6:9]
	v_mfma_f32_16x16x32_bf16 v[18:21], v[130:133], v[204:207], v[18:21]
	v_mfma_f32_16x16x32_bf16 v[26:29], v[138:141], v[204:207], v[26:29]
	v_mfma_f32_16x16x32_bf16 v[34:37], v[130:133], v[226:229], v[34:37]
	v_mfma_f32_16x16x32_bf16 v[42:45], v[138:141], v[226:229], v[42:45]
	v_mfma_f32_16x16x32_bf16 v[50:53], v[130:133], v[234:237], v[50:53]
	v_mfma_f32_16x16x32_bf16 v[58:61], v[138:141], v[234:237], v[58:61]
	v_mfma_f32_16x16x32_bf16 v[2:5], v[134:137], v[200:203], v[2:5]
	v_mfma_f32_16x16x32_bf16 v[6:9], v[142:145], v[200:203], v[6:9]
	v_mfma_f32_16x16x32_bf16 v[18:21], v[134:137], v[208:211], v[18:21]
	v_mfma_f32_16x16x32_bf16 v[26:29], v[142:145], v[208:211], v[26:29]
	v_mfma_f32_16x16x32_bf16 v[34:37], v[134:137], v[230:233], v[34:37]
	v_mfma_f32_16x16x32_bf16 v[42:45], v[142:145], v[230:233], v[42:45]
	v_mfma_f32_16x16x32_bf16 v[50:53], v[134:137], v[238:241], v[50:53]
	v_mfma_f32_16x16x32_bf16 v[58:61], v[142:145], v[238:241], v[58:61]
	v_mfma_f32_16x16x32_bf16 v[10:13], v[180:183], v[196:199], v[10:13]
	v_mfma_f32_16x16x32_bf16 v[14:17], v[188:191], v[196:199], v[14:17]
	v_mfma_f32_16x16x32_bf16 v[22:25], v[180:183], v[204:207], v[22:25]
	v_mfma_f32_16x16x32_bf16 v[30:33], v[188:191], v[204:207], v[30:33]
	v_mfma_f32_16x16x32_bf16 v[38:41], v[180:183], v[226:229], v[38:41]
	v_mfma_f32_16x16x32_bf16 v[46:49], v[188:191], v[226:229], v[46:49]
	v_mfma_f32_16x16x32_bf16 v[54:57], v[180:183], v[234:237], v[54:57]
	v_mfma_f32_16x16x32_bf16 v[62:65], v[188:191], v[234:237], v[62:65]
	v_mfma_f32_16x16x32_bf16 v[10:13], v[184:187], v[200:203], v[10:13]
	v_mfma_f32_16x16x32_bf16 v[14:17], v[192:195], v[200:203], v[14:17]
	v_mfma_f32_16x16x32_bf16 v[22:25], v[184:187], v[208:211], v[22:25]
	v_mfma_f32_16x16x32_bf16 v[30:33], v[192:195], v[208:211], v[30:33]
	v_mfma_f32_16x16x32_bf16 v[38:41], v[184:187], v[230:233], v[38:41]
	v_mfma_f32_16x16x32_bf16 v[46:49], v[192:195], v[230:233], v[46:49]
	v_mfma_f32_16x16x32_bf16 v[54:57], v[184:187], v[238:241], v[54:57]
	v_mfma_f32_16x16x32_bf16 v[62:65], v[192:195], v[238:241], v[62:65]
	s_setprio 0
	s_barrier
; #define PG8_STAGE(bufoff, gbase) do { _Pragma("unroll") for (int _i = 0; _i < 2; ++_i) \
;         __builtin_amdgcn_global_load_lds((const unsigned*)((const char*)(gbase) + voffA[_i]), (LAS unsigned*)(lds + (bufoff) + ldsw + _i * 8192), 16, 0, 0); } while (0)
; #define PG8_LDA(dst, b, h) do { _Pragma("unroll") for (int m = 0; m < 4; ++m) _Pragma("unroll") for (int k = 0; k < 2; ++k) dst[m][k] = *(const LAS bf16x8*)(lds + PG8_SA(b, h) + aoff + m * 2048 + k * 1024); } while (0)
; #define PG8_MMA(ai, bj, At, Bt) do { __builtin_amdgcn_s_setprio(1); _Pragma("unroll") for (int m = 0; m < 4; ++m) _Pragma("unroll") for (int n = 0; n < 2; ++n) _Pragma("unroll") for (int k = 0; k < 2; ++k) \
;         acc[ai][bj][m][n] = __builtin_amdgcn_mfma_f32_16x16x32_bf16(Bt[n][k], At[m][k], acc[ai][bj][m][n], 0, 0, 0); __builtin_amdgcn_s_setprio(0); } while (0)
; #define PG8_WAIT_V(n) asm volatile("s_waitcnt vmcnt(" #n ")" ::: "memory")
; #define PG8_WAIT_L(n) asm volatile("s_waitcnt lgkmcnt(" #n ")" ::: "memory")
; #define PG8_BAR __builtin_amdgcn_s_barrier()
; #define PG8_SCHED __builtin_amdgcn_sched_barrier(0)
; template <class Epi, class Sched>
; __device__ __forceinline__ void gemm_phase(LAS unsigned char* lds, const Gemm g, const Sched& S, const Epi& E) {
;     ...
;             PG8_LDA(At, 1, 1); PG8_STAGE(PG8_SB(1, 0), b3); PG8_STAGE(PG8_SB(1, 1), b3 + hstep); PG8_STAGE(PG8_SA(1, 0), a3);
;             PG8_WAIT_V(8); PG8_WAIT_L(0); PG8_BAR; PG8_MMA(1, 0, At, B0); PG8_MMA(1, 1, At, B1); PG8_BAR; PG8_SCHED;
;         }
	s_add_i32 s72, s99, s56
	v_lshl_add_u64 v[216:217], v[242:243], 0, s[26:27]
	s_mov_b32 m0, s72
	ds_read_b128 v[196:199], v224 offset:49152
	ds_read_b128 v[200:203], v224 offset:50176
	ds_read_b128 v[204:207], v224 offset:51200
	ds_read_b128 v[208:211], v224 offset:52224
	ds_read_b128 v[226:229], v224 offset:53248
	ds_read_b128 v[230:233], v224 offset:54272
	ds_read_b128 v[234:237], v224 offset:55296
	ds_read_b128 v[238:241], v224 offset:56320
	global_load_lds_dwordx4 v[216:217], off
	v_lshl_add_u64 v[216:217], v[244:245], 0, s[26:27]
	s_add_i32 m0, s72, 0x2000
	s_add_i32 s72, s94, s56
	global_load_lds_dwordx4 v[216:217], off
	v_lshl_add_u64 v[216:217], v[246:247], 0, s[26:27]
	s_mov_b32 m0, s72
	s_nop 0
	global_load_lds_dwordx4 v[216:217], off
	v_lshl_add_u64 v[216:217], v[248:249], 0, s[26:27]
	s_add_i32 m0, s72, 0x2000
	s_nop 0
	global_load_lds_dwordx4 v[216:217], off
	v_lshl_add_u64 v[216:217], v[250:251], 0, s[26:27]
	s_mov_b32 m0, s88
	s_nop 0
	global_load_lds_dwordx4 v[216:217], off
	v_lshl_add_u64 v[216:217], v[252:253], 0, s[26:27]
	s_mov_b32 m0, s89
	s_nop 0
	global_load_lds_dwordx4 v[216:217], off
	s_waitcnt vmcnt(8)
	s_waitcnt lgkmcnt(0)
	s_barrier
	s_setprio 1
	s_waitcnt lgkmcnt(0)
	v_mfma_f32_16x16x32_bf16 v[66:69], v[130:133], v[196:199], v[66:69]
	v_mfma_f32_16x16x32_bf16 v[74:77], v[138:141], v[196:199], v[74:77]
	v_mfma_f32_16x16x32_bf16 v[82:85], v[130:133], v[204:207], v[82:85]
	v_mfma_f32_16x16x32_bf16 v[90:93], v[138:141], v[204:207], v[90:93]
	v_mfma_f32_16x16x32_bf16 v[98:101], v[130:133], v[226:229], v[98:101]
	v_mfma_f32_16x16x32_bf16 v[106:109], v[138:141], v[226:229], v[106:109]
	v_mfma_f32_16x16x32_bf16 v[114:117], v[130:133], v[234:237], v[114:117]
	v_mfma_f32_16x16x32_bf16 v[122:125], v[138:141], v[234:237], v[122:125]
	v_mfma_f32_16x16x32_bf16 v[66:69], v[134:137], v[200:203], v[66:69]
	v_mfma_f32_16x16x32_bf16 v[74:77], v[142:145], v[200:203], v[74:77]
	v_mfma_f32_16x16x32_bf16 v[82:85], v[134:137], v[208:211], v[82:85]
	v_mfma_f32_16x16x32_bf16 v[90:93], v[142:145], v[208:211], v[90:93]
	v_mfma_f32_16x16x32_bf16 v[98:101], v[134:137], v[230:233], v[98:101]
	v_mfma_f32_16x16x32_bf16 v[106:109], v[142:145], v[230:233], v[106:109]
	v_mfma_f32_16x16x32_bf16 v[114:117], v[134:137], v[238:241], v[114:117]
	v_mfma_f32_16x16x32_bf16 v[122:125], v[142:145], v[238:241], v[122:125]
	v_mfma_f32_16x16x32_bf16 v[70:73], v[180:183], v[196:199], v[70:73]
	v_mfma_f32_16x16x32_bf16 v[78:81], v[188:191], v[196:199], v[78:81]
	v_mfma_f32_16x16x32_bf16 v[86:89], v[180:183], v[204:207], v[86:89]
	v_mfma_f32_16x16x32_bf16 v[94:97], v[188:191], v[204:207], v[94:97]
	v_mfma_f32_16x16x32_bf16 v[102:105], v[180:183], v[226:229], v[102:105]
	v_mfma_f32_16x16x32_bf16 v[110:113], v[188:191], v[226:229], v[110:113]
	v_mfma_f32_16x16x32_bf16 v[118:121], v[180:183], v[234:237], v[118:121]
	v_mfma_f32_16x16x32_bf16 v[126:129], v[188:191], v[234:237], v[126:129]
	v_mfma_f32_16x16x32_bf16 v[70:73], v[184:187], v[200:203], v[70:73]
	v_mfma_f32_16x16x32_bf16 v[78:81], v[192:195], v[200:203], v[78:81]
	v_mfma_f32_16x16x32_bf16 v[86:89], v[184:187], v[208:211], v[86:89]
	v_mfma_f32_16x16x32_bf16 v[94:97], v[192:195], v[208:211], v[94:97]
	v_mfma_f32_16x16x32_bf16 v[102:105], v[184:187], v[230:233], v[102:105]
	v_mfma_f32_16x16x32_bf16 v[110:113], v[192:195], v[230:233], v[110:113]
	v_mfma_f32_16x16x32_bf16 v[118:121], v[184:187], v[238:241], v[118:121]
	v_mfma_f32_16x16x32_bf16 v[126:129], v[192:195], v[238:241], v[126:129]
	s_setprio 0
	s_barrier
	s_add_u32 s46, s46, 0x100
	s_addc_u32 s47, s47, 0
	s_add_u32 s70, s70, 0x100
	s_addc_u32 s71, s71, 0
	s_cmp_ge_u32 s93, s1
	s_mov_b32 s72, s93
	s_cbranch_scc0 .LBB0_292
	s_and_b64 vcc, exec, s[60:61]
	s_cbranch_vccz .LBB0_295
	s_barrier

; #define PG8_STAGE(bufoff, gbase) do { _Pragma("unroll") for (int _i = 0; _i < 2; ++_i) \
;         __builtin_amdgcn_global_load_lds((const unsigned*)((const char*)(gbase) + voffA[_i]), (LAS unsigned*)(lds + (bufoff) + ldsw + _i * 8192), 16, 0, 0); } while (0)
; #define PG8_LDA(dst, b, h) do { _Pragma("unroll") for (int m = 0; m < 4; ++m) _Pragma("unroll") for (int k = 0; k < 2; ++k) dst[m][k] = *(const LAS bf16x8*)(lds + PG8_SA(b, h) + aoff + m * 2048 + k * 1024); } while (0)
; #define PG8_LDB(dst, b, h) do { _Pragma("unroll") for (int n = 0; n < 2; ++n) _Pragma("unroll") for (int k = 0; k < 2; ++k) dst[n][k] = *(const LAS bf16x8*)(lds + PG8_SB(b, h) + boff + n * 2048 + k * 1024); } while (0)
; #define PG8_MMA(ai, bj, At, Bt) do { __builtin_amdgcn_s_setprio(1); _Pragma("unroll") for (int m = 0; m < 4; ++m) _Pragma("unroll") for (int n = 0; n < 2; ++n) _Pragma("unroll") for (int k = 0; k < 2; ++k) \
;         acc[ai][bj][m][n] = __builtin_amdgcn_mfma_f32_16x16x32_bf16(Bt[n][k], At[m][k], acc[ai][bj][m][n], 0, 0, 0); __builtin_amdgcn_s_setprio(0); } while (0)
; #define PG8_WAIT_V(n) asm volatile("s_waitcnt vmcnt(" #n ")" ::: "memory")
; #define PG8_WAIT_L(n) asm volatile("s_waitcnt lgkmcnt(" #n ")" ::: "memory")
; #define PG8_BAR __builtin_amdgcn_s_barrier()
; #define PG8_SCHED __builtin_amdgcn_sched_barrier(0)
; template <class Epi, class Sched>
; __device__ __forceinline__ void gemm_phase(LAS unsigned char* lds, const Gemm g, const Sched& S, const Epi& E) {
;     ...
;         for (int t = 0; t < nt; t += 2) {
;             const bool last = (t == nt - 2);
;             const char* a1 = cA + (size_t)(t + 1) * kstep;
;             const char* a2 = last ? nA : cA + (size_t)(t + 2) * kstep; const char* b2 = last ? nB : cB + (size_t)(t + 2) * kstep;
;             const char* a3 = a2 + kstep; const char* b3 = b2 + kstep;
;             PG8_LDB(B0, 0, 0); PG8_LDB(B1, 0, 1); PG8_SCHED; PG8_LDA(At, 0, 0); PG8_STAGE(PG8_SA(1, 1), a1 + hstep);
;             PG8_WAIT_V(8); PG8_WAIT_L(0); PG8_BAR; PG8_MMA(0, 0, At, B0); PG8_MMA(0, 1, At, B1); PG8_BAR; PG8_SCHED;
;             PG8_LDA(At, 0, 1); PG8_STAGE(PG8_SB(0, 0), b2); PG8_STAGE(PG8_SB(0, 1), b2 + hstep); PG8_STAGE(PG8_SA(0, 0), a2);
;             PG8_WAIT_V(8); PG8_WAIT_L(0); PG8_BAR; PG8_MMA(1, 0, At, B0); PG8_MMA(1, 1, At, B1); PG8_BAR; PG8_SCHED;
.LBB0_339:
	s_add_u32 s62, s44, 0x100
	s_addc_u32 s63, s45, 0
	s_add_i32 s88, 0, 0x10000
	s_cmpk_eq_i32 s85, 0x52
	s_cselect_b32 s67, s47, s63
	s_cselect_b32 s66, s46, s62
	s_cselect_b32 s65, s15, s84
	s_cselect_b32 s64, s14, s75
	s_add_i32 s89, 0, 0x14000
	v_add_u32_e32 v142, s88, v209
	v_add_u32_e32 v188, s89, v209
	ds_read_b128 v[130:133], v142
	ds_read_b128 v[134:137], v142 offset:1024
	ds_read_b128 v[138:141], v142 offset:2048
	ds_read_b128 v[142:145], v142 offset:3072
	ds_read_b128 v[176:179], v188
	ds_read_b128 v[180:183], v188 offset:1024
	ds_read_b128 v[184:187], v188 offset:2048
	ds_read_b128 v[188:191], v188 offset:3072
	v_lshl_add_u64 v[238:239], s[44:45], 0, v[172:173]
	s_add_i32 m0, s2, 0xc000
	ds_read_b128 v[192:195], v210
	ds_read_b128 v[196:199], v210 offset:1024
	ds_read_b128 v[200:203], v210 offset:2048
	ds_read_b128 v[204:207], v210 offset:3072
	ds_read_b128 v[222:225], v210 offset:4096
	ds_read_b128 v[226:229], v210 offset:5120
	ds_read_b128 v[230:233], v210 offset:6144
	ds_read_b128 v[234:237], v210 offset:7168
	global_load_lds_dwordx4 v[238:239], off
	v_lshl_add_u64 v[238:239], s[44:45], 0, v[174:175]
	s_add_i32 m0, s2, 0xe000
	s_nop 0
	global_load_lds_dwordx4 v[238:239], off
	s_waitcnt vmcnt(8)
	s_waitcnt lgkmcnt(0)
	s_barrier
	s_setprio 1
	s_waitcnt lgkmcnt(0)
	v_mfma_f32_16x16x32_bf16 v[126:129], v[130:133], v[192:195], v[126:129]
	v_mfma_f32_16x16x32_bf16 v[122:125], v[138:141], v[192:195], v[122:125]
	v_mfma_f32_16x16x32_bf16 v[110:113], v[130:133], v[200:203], v[110:113]
	v_mfma_f32_16x16x32_bf16 v[106:109], v[138:141], v[200:203], v[106:109]
	v_mfma_f32_16x16x32_bf16 v[94:97], v[130:133], v[222:225], v[94:97]
	v_mfma_f32_16x16x32_bf16 v[90:93], v[138:141], v[222:225], v[90:93]
	v_mfma_f32_16x16x32_bf16 v[78:81], v[130:133], v[230:233], v[78:81]
	v_mfma_f32_16x16x32_bf16 v[74:77], v[138:141], v[230:233], v[74:77]
	v_mfma_f32_16x16x32_bf16 v[126:129], v[134:137], v[196:199], v[126:129]
	v_mfma_f32_16x16x32_bf16 v[122:125], v[142:145], v[196:199], v[122:125]
	v_mfma_f32_16x16x32_bf16 v[110:113], v[134:137], v[204:207], v[110:113]
	v_mfma_f32_16x16x32_bf16 v[106:109], v[142:145], v[204:207], v[106:109]
	v_mfma_f32_16x16x32_bf16 v[94:97], v[134:137], v[226:229], v[94:97]
	v_mfma_f32_16x16x32_bf16 v[90:93], v[142:145], v[226:229], v[90:93]
	v_mfma_f32_16x16x32_bf16 v[78:81], v[134:137], v[234:237], v[78:81]
	v_mfma_f32_16x16x32_bf16 v[74:77], v[142:145], v[234:237], v[74:77]
	v_mfma_f32_16x16x32_bf16 v[118:121], v[176:179], v[192:195], v[118:121]
	v_mfma_f32_16x16x32_bf16 v[114:117], v[184:187], v[192:195], v[114:117]
	v_mfma_f32_16x16x32_bf16 v[102:105], v[176:179], v[200:203], v[102:105]
	v_mfma_f32_16x16x32_bf16 v[98:101], v[184:187], v[200:203], v[98:101]
	v_mfma_f32_16x16x32_bf16 v[86:89], v[176:179], v[222:225], v[86:89]
	v_mfma_f32_16x16x32_bf16 v[82:85], v[184:187], v[222:225], v[82:85]
	v_mfma_f32_16x16x32_bf16 v[70:73], v[176:179], v[230:233], v[70:73]
	v_mfma_f32_16x16x32_bf16 v[66:69], v[184:187], v[230:233], v[66:69]
	v_mfma_f32_16x16x32_bf16 v[118:121], v[180:183], v[196:199], v[118:121]
	v_mfma_f32_16x16x32_bf16 v[114:117], v[188:191], v[196:199], v[114:117]
	v_mfma_f32_16x16x32_bf16 v[102:105], v[180:183], v[204:207], v[102:105]
	v_mfma_f32_16x16x32_bf16 v[98:101], v[188:191], v[204:207], v[98:101]
	v_mfma_f32_16x16x32_bf16 v[86:89], v[180:183], v[226:229], v[86:89]
	v_mfma_f32_16x16x32_bf16 v[82:85], v[188:191], v[226:229], v[82:85]
	v_mfma_f32_16x16x32_bf16 v[70:73], v[180:183], v[234:237], v[70:73]
	v_mfma_f32_16x16x32_bf16 v[66:69], v[188:191], v[234:237], v[66:69]
	s_setprio 0
	s_barrier
	s_add_i32 s44, s88, s33
	v_lshl_add_u64 v[238:239], s[64:65], 0, v[0:1]
	s_mov_b32 m0, s44
	ds_read_b128 v[192:195], v210 offset:16384
	ds_read_b128 v[196:199], v210 offset:17408
	ds_read_b128 v[200:203], v210 offset:18432
	ds_read_b128 v[204:207], v210 offset:19456
	ds_read_b128 v[222:225], v210 offset:20480
	ds_read_b128 v[226:229], v210 offset:21504
	ds_read_b128 v[230:233], v210 offset:22528
	ds_read_b128 v[234:237], v210 offset:23552
	global_load_lds_dwordx4 v[238:239], off
	s_add_i32 m0, s44, 0x2000
	s_add_u32 s44, s64, 0x158000
	v_lshl_add_u64 v[240:241], s[64:65], 0, v[164:165]
	s_addc_u32 s45, s65, 0
	s_add_i32 s88, s89, s33
	global_load_lds_dwordx4 v[240:241], off
	v_lshl_add_u64 v[242:243], s[44:45], 0, v[0:1]
	s_mov_b32 m0, s88
	v_lshl_add_u64 v[244:245], s[66:67], 0, v[164:165]
	global_load_lds_dwordx4 v[242:243], off
	v_lshl_add_u64 v[242:243], s[44:45], 0, v[164:165]
	s_add_i32 m0, s88, 0x2000
	s_nop 0
	global_load_lds_dwordx4 v[242:243], off
	v_lshl_add_u64 v[242:243], s[66:67], 0, v[0:1]
	s_mov_b32 m0, s2
	s_nop 0
	global_load_lds_dwordx4 v[242:243], off
	s_mov_b32 m0, s36
	s_nop 0
	global_load_lds_dwordx4 v[244:245], off
	s_waitcnt vmcnt(8)
	s_waitcnt lgkmcnt(0)
	s_barrier
; #define PG8_STAGE(bufoff, gbase) do { _Pragma("unroll") for (int _i = 0; _i < 2; ++_i) \
;         __builtin_amdgcn_global_load_lds((const unsigned*)((const char*)(gbase) + voffA[_i]), (LAS unsigned*)(lds + (bufoff) + ldsw + _i * 8192), 16, 0, 0); } while (0)
; #define PG8_LDA(dst, b, h) do { _Pragma("unroll") for (int m = 0; m < 4; ++m) _Pragma("unroll") for (int k = 0; k < 2; ++k) dst[m][k] = *(const LAS bf16x8*)(lds + PG8_SA(b, h) + aoff + m * 2048 + k * 1024); } while (0)
; #define PG8_LDB(dst, b, h) do { _Pragma("unroll") for (int n = 0; n < 2; ++n) _Pragma("unroll") for (int k = 0; k < 2; ++k) dst[n][k] = *(const LAS bf16x8*)(lds + PG8_SB(b, h) + boff + n * 2048 + k * 1024); } while (0)
; #define PG8_MMA(ai, bj, At, Bt) do { __builtin_amdgcn_s_setprio(1); _Pragma("unroll") for (int m = 0; m < 4; ++m) _Pragma("unroll") for (int n = 0; n < 2; ++n) _Pragma("unroll") for (int k = 0; k < 2; ++k) \
;         acc[ai][bj][m][n] = __builtin_amdgcn_mfma_f32_16x16x32_bf16(Bt[n][k], At[m][k], acc[ai][bj][m][n], 0, 0, 0); __builtin_amdgcn_s_setprio(0); } while (0)
; #define PG8_WAIT_V(n) asm volatile("s_waitcnt vmcnt(" #n ")" ::: "memory")
; #define PG8_WAIT_L(n) asm volatile("s_waitcnt lgkmcnt(" #n ")" ::: "memory")
; #define PG8_BAR __builtin_amdgcn_s_barrier()
; #define PG8_SCHED __builtin_amdgcn_sched_barrier(0)
; template <class Epi, class Sched>
; __device__ __forceinline__ void gemm_phase(LAS unsigned char* lds, const Gemm g, const Sched& S, const Epi& E) {
;     ...
;             PG8_WAIT_V(8); PG8_WAIT_L(0); PG8_BAR; PG8_MMA(1, 0, At, B0); PG8_MMA(1, 1, At, B1); PG8_BAR; PG8_SCHED;
;             PG8_LDB(B0, 1, 0); PG8_LDB(B1, 1, 1); PG8_SCHED; PG8_LDA(At, 1, 0); PG8_STAGE(PG8_SA(0, 1), a2 + hstep);
;             PG8_WAIT_V(8); PG8_WAIT_L(0); PG8_BAR; PG8_MMA(0, 0, At, B0); PG8_MMA(0, 1, At, B1); PG8_BAR; PG8_SCHED;
	s_setprio 1
	s_waitcnt lgkmcnt(0)
	v_mfma_f32_16x16x32_bf16 v[62:65], v[130:133], v[192:195], v[62:65]
	v_mfma_f32_16x16x32_bf16 v[58:61], v[138:141], v[192:195], v[58:61]
	v_mfma_f32_16x16x32_bf16 v[46:49], v[130:133], v[200:203], v[46:49]
	v_mfma_f32_16x16x32_bf16 v[42:45], v[138:141], v[200:203], v[42:45]
	v_mfma_f32_16x16x32_bf16 v[30:33], v[130:133], v[222:225], v[30:33]
	v_mfma_f32_16x16x32_bf16 v[26:29], v[138:141], v[222:225], v[26:29]
	v_mfma_f32_16x16x32_bf16 v[14:17], v[130:133], v[230:233], v[14:17]
	v_mfma_f32_16x16x32_bf16 v[10:13], v[138:141], v[230:233], v[10:13]
	v_mfma_f32_16x16x32_bf16 v[62:65], v[134:137], v[196:199], v[62:65]
	v_mfma_f32_16x16x32_bf16 v[58:61], v[142:145], v[196:199], v[58:61]
	v_mfma_f32_16x16x32_bf16 v[46:49], v[134:137], v[204:207], v[46:49]
	v_mfma_f32_16x16x32_bf16 v[42:45], v[142:145], v[204:207], v[42:45]
	v_mfma_f32_16x16x32_bf16 v[30:33], v[134:137], v[226:229], v[30:33]
	v_mfma_f32_16x16x32_bf16 v[26:29], v[142:145], v[226:229], v[26:29]
	v_mfma_f32_16x16x32_bf16 v[14:17], v[134:137], v[234:237], v[14:17]
	v_mfma_f32_16x16x32_bf16 v[10:13], v[142:145], v[234:237], v[10:13]
	v_mfma_f32_16x16x32_bf16 v[54:57], v[176:179], v[192:195], v[54:57]
	v_mfma_f32_16x16x32_bf16 v[50:53], v[184:187], v[192:195], v[50:53]
	v_mfma_f32_16x16x32_bf16 v[38:41], v[176:179], v[200:203], v[38:41]
	v_mfma_f32_16x16x32_bf16 v[34:37], v[184:187], v[200:203], v[34:37]
	v_mfma_f32_16x16x32_bf16 v[22:25], v[176:179], v[222:225], v[22:25]
	v_mfma_f32_16x16x32_bf16 v[18:21], v[184:187], v[222:225], v[18:21]
	v_mfma_f32_16x16x32_bf16 v[6:9], v[176:179], v[230:233], v[6:9]
	v_mfma_f32_16x16x32_bf16 v[2:5], v[184:187], v[230:233], v[2:5]
	v_mfma_f32_16x16x32_bf16 v[54:57], v[180:183], v[196:199], v[54:57]
	v_mfma_f32_16x16x32_bf16 v[50:53], v[188:191], v[196:199], v[50:53]
	v_mfma_f32_16x16x32_bf16 v[38:41], v[180:183], v[204:207], v[38:41]
	v_mfma_f32_16x16x32_bf16 v[34:37], v[188:191], v[204:207], v[34:37]
	v_mfma_f32_16x16x32_bf16 v[22:25], v[180:183], v[226:229], v[22:25]
	v_mfma_f32_16x16x32_bf16 v[18:21], v[188:191], v[226:229], v[18:21]
	v_mfma_f32_16x16x32_bf16 v[6:9], v[180:183], v[234:237], v[6:9]
	v_mfma_f32_16x16x32_bf16 v[2:5], v[188:191], v[234:237], v[2:5]
	s_setprio 0
	s_barrier
	s_add_i32 s88, 0, 0x1c000
	v_add_u32_e32 v142, s99, v209
	v_add_u32_e32 v188, s88, v209
	ds_read_b128 v[130:133], v142
	ds_read_b128 v[134:137], v142 offset:1024
	ds_read_b128 v[138:141], v142 offset:2048
	ds_read_b128 v[142:145], v142 offset:3072
	ds_read_b128 v[176:179], v188
	ds_read_b128 v[180:183], v188 offset:1024
	ds_read_b128 v[184:187], v188 offset:2048
	ds_read_b128 v[188:191], v188 offset:3072
	s_add_u32 s44, s66, 0x158000
	s_addc_u32 s45, s67, 0
	s_mov_b32 m0, s38
	v_lshl_add_u64 v[246:247], s[44:45], 0, v[0:1]
	ds_read_b128 v[192:195], v210 offset:32768
	ds_read_b128 v[196:199], v210 offset:33792
	ds_read_b128 v[200:203], v210 offset:34816
	ds_read_b128 v[204:207], v210 offset:35840
	ds_read_b128 v[222:225], v210 offset:36864
	ds_read_b128 v[226:229], v210 offset:37888
	ds_read_b128 v[230:233], v210 offset:38912
	ds_read_b128 v[234:237], v210 offset:39936
	global_load_lds_dwordx4 v[246:247], off
	v_lshl_add_u64 v[246:247], s[44:45], 0, v[164:165]
	s_mov_b32 m0, s39
	s_nop 0
	global_load_lds_dwordx4 v[246:247], off
	s_waitcnt vmcnt(8)
	s_waitcnt lgkmcnt(0)
	s_barrier
	s_setprio 1
	s_waitcnt lgkmcnt(0)
	v_mfma_f32_16x16x32_bf16 v[126:129], v[130:133], v[192:195], v[126:129]
	v_mfma_f32_16x16x32_bf16 v[122:125], v[138:141], v[192:195], v[122:125]
	v_mfma_f32_16x16x32_bf16 v[110:113], v[130:133], v[200:203], v[110:113]
	v_mfma_f32_16x16x32_bf16 v[106:109], v[138:141], v[200:203], v[106:109]
	v_mfma_f32_16x16x32_bf16 v[94:97], v[130:133], v[222:225], v[94:97]
	v_mfma_f32_16x16x32_bf16 v[90:93], v[138:141], v[222:225], v[90:93]
	v_mfma_f32_16x16x32_bf16 v[78:81], v[130:133], v[230:233], v[78:81]
	v_mfma_f32_16x16x32_bf16 v[74:77], v[138:141], v[230:233], v[74:77]
	v_mfma_f32_16x16x32_bf16 v[126:129], v[134:137], v[196:199], v[126:129]
	v_mfma_f32_16x16x32_bf16 v[122:125], v[142:145], v[196:199], v[122:125]
	v_mfma_f32_16x16x32_bf16 v[110:113], v[134:137], v[204:207], v[110:113]
	v_mfma_f32_16x16x32_bf16 v[106:109], v[142:145], v[204:207], v[106:109]
	v_mfma_f32_16x16x32_bf16 v[94:97], v[134:137], v[226:229], v[94:97]
	v_mfma_f32_16x16x32_bf16 v[90:93], v[142:145], v[226:229], v[90:93]
	v_mfma_f32_16x16x32_bf16 v[78:81], v[134:137], v[234:237], v[78:81]
	v_mfma_f32_16x16x32_bf16 v[74:77], v[142:145], v[234:237], v[74:77]
	v_mfma_f32_16x16x32_bf16 v[118:121], v[176:179], v[192:195], v[118:121]
	v_mfma_f32_16x16x32_bf16 v[114:117], v[184:187], v[192:195], v[114:117]
	v_mfma_f32_16x16x32_bf16 v[102:105], v[176:179], v[200:203], v[102:105]
	v_mfma_f32_16x16x32_bf16 v[98:101], v[184:187], v[200:203], v[98:101]
	v_mfma_f32_16x16x32_bf16 v[86:89], v[176:179], v[222:225], v[86:89]
	v_mfma_f32_16x16x32_bf16 v[82:85], v[184:187], v[222:225], v[82:85]
	v_mfma_f32_16x16x32_bf16 v[70:73], v[176:179], v[230:233], v[70:73]
	v_mfma_f32_16x16x32_bf16 v[66:69], v[184:187], v[230:233], v[66:69]
	v_mfma_f32_16x16x32_bf16 v[118:121], v[180:183], v[196:199], v[118:121]
	v_mfma_f32_16x16x32_bf16 v[114:117], v[188:191], v[196:199], v[114:117]
	v_mfma_f32_16x16x32_bf16 v[102:105], v[180:183], v[204:207], v[102:105]
	v_mfma_f32_16x16x32_bf16 v[98:101], v[188:191], v[204:207], v[98:101]
	v_mfma_f32_16x16x32_bf16 v[86:89], v[180:183], v[226:229], v[86:89]
	v_mfma_f32_16x16x32_bf16 v[82:85], v[188:191], v[226:229], v[82:85]
	v_mfma_f32_16x16x32_bf16 v[70:73], v[180:183], v[234:237], v[70:73]
	v_mfma_f32_16x16x32_bf16 v[66:69], v[188:191], v[234:237], v[66:69]
	s_setprio 0
	s_barrier
; #define PG8_STAGE(bufoff, gbase) do { _Pragma("unroll") for (int _i = 0; _i < 2; ++_i) \
;         __builtin_amdgcn_global_load_lds((const unsigned*)((const char*)(gbase) + voffA[_i]), (LAS unsigned*)(lds + (bufoff) + ldsw + _i * 8192), 16, 0, 0); } while (0)
; #define PG8_LDA(dst, b, h) do { _Pragma("unroll") for (int m = 0; m < 4; ++m) _Pragma("unroll") for (int k = 0; k < 2; ++k) dst[m][k] = *(const LAS bf16x8*)(lds + PG8_SA(b, h) + aoff + m * 2048 + k * 1024); } while (0)
; #define PG8_MMA(ai, bj, At, Bt) do { __builtin_amdgcn_s_setprio(1); _Pragma("unroll") for (int m = 0; m < 4; ++m) _Pragma("unroll") for (int n = 0; n < 2; ++n) _Pragma("unroll") for (int k = 0; k < 2; ++k) \
;         acc[ai][bj][m][n] = __builtin_amdgcn_mfma_f32_16x16x32_bf16(Bt[n][k], At[m][k], acc[ai][bj][m][n], 0, 0, 0); __builtin_amdgcn_s_setprio(0); } while (0)
; #define PG8_WAIT_V(n) asm volatile("s_waitcnt vmcnt(" #n ")" ::: "memory")
; #define PG8_WAIT_L(n) asm volatile("s_waitcnt lgkmcnt(" #n ")" ::: "memory")
; #define PG8_BAR __builtin_amdgcn_s_barrier()
; #define PG8_SCHED __builtin_amdgcn_sched_barrier(0)
; template <class Epi, class Sched>
; __device__ __forceinline__ void gemm_phase(LAS unsigned char* lds, const Gemm g, const Sched& S, const Epi& E) {
;     ...
;             PG8_LDA(At, 1, 1); PG8_STAGE(PG8_SB(1, 0), b3); PG8_STAGE(PG8_SB(1, 1), b3 + hstep); PG8_STAGE(PG8_SA(1, 0), a3);
;             PG8_WAIT_V(8); PG8_WAIT_L(0); PG8_BAR; PG8_MMA(1, 0, At, B0); PG8_MMA(1, 1, At, B1); PG8_BAR; PG8_SCHED;
;         }
	s_add_i32 s44, s99, s33
	v_lshl_add_u64 v[238:239], v[238:239], 0, s[26:27]
	s_mov_b32 m0, s44
	ds_read_b128 v[192:195], v210 offset:49152
	ds_read_b128 v[196:199], v210 offset:50176
	ds_read_b128 v[200:203], v210 offset:51200
	ds_read_b128 v[204:207], v210 offset:52224
	ds_read_b128 v[222:225], v210 offset:53248
	ds_read_b128 v[226:229], v210 offset:54272
	ds_read_b128 v[230:233], v210 offset:55296
	ds_read_b128 v[234:237], v210 offset:56320
	global_load_lds_dwordx4 v[238:239], off
	s_add_i32 m0, s44, 0x2000
	s_add_u32 s44, s64, 0x158080
	v_lshl_add_u64 v[238:239], v[240:241], 0, s[26:27]
	s_addc_u32 s45, s65, 0
	s_add_i32 s64, s88, s33
	global_load_lds_dwordx4 v[238:239], off
	v_lshl_add_u64 v[238:239], s[44:45], 0, v[0:1]
	s_mov_b32 m0, s64
	s_nop 0
	global_load_lds_dwordx4 v[238:239], off
	v_lshl_add_u64 v[238:239], s[44:45], 0, v[164:165]
	s_add_i32 m0, s64, 0x2000
	s_nop 0
	global_load_lds_dwordx4 v[238:239], off
	v_lshl_add_u64 v[238:239], v[242:243], 0, s[26:27]
	s_mov_b32 m0, s56
	s_nop 0
	global_load_lds_dwordx4 v[238:239], off
	v_lshl_add_u64 v[238:239], v[244:245], 0, s[26:27]
	s_mov_b32 m0, s68
	s_nop 0
	global_load_lds_dwordx4 v[238:239], off
	s_waitcnt vmcnt(8)
	s_waitcnt lgkmcnt(0)
	s_barrier
	s_setprio 1
	s_waitcnt lgkmcnt(0)
	v_mfma_f32_16x16x32_bf16 v[62:65], v[130:133], v[192:195], v[62:65]
	v_mfma_f32_16x16x32_bf16 v[58:61], v[138:141], v[192:195], v[58:61]
	v_mfma_f32_16x16x32_bf16 v[46:49], v[130:133], v[200:203], v[46:49]
	v_mfma_f32_16x16x32_bf16 v[42:45], v[138:141], v[200:203], v[42:45]
	v_mfma_f32_16x16x32_bf16 v[30:33], v[130:133], v[222:225], v[30:33]
	v_mfma_f32_16x16x32_bf16 v[26:29], v[138:141], v[222:225], v[26:29]
	v_mfma_f32_16x16x32_bf16 v[14:17], v[130:133], v[230:233], v[14:17]
	v_mfma_f32_16x16x32_bf16 v[10:13], v[138:141], v[230:233], v[10:13]
	v_mfma_f32_16x16x32_bf16 v[62:65], v[134:137], v[196:199], v[62:65]
	v_mfma_f32_16x16x32_bf16 v[58:61], v[142:145], v[196:199], v[58:61]
	v_mfma_f32_16x16x32_bf16 v[46:49], v[134:137], v[204:207], v[46:49]
	v_mfma_f32_16x16x32_bf16 v[42:45], v[142:145], v[204:207], v[42:45]
	v_mfma_f32_16x16x32_bf16 v[30:33], v[134:137], v[226:229], v[30:33]
	v_mfma_f32_16x16x32_bf16 v[26:29], v[142:145], v[226:229], v[26:29]
	v_mfma_f32_16x16x32_bf16 v[14:17], v[134:137], v[234:237], v[14:17]
	v_mfma_f32_16x16x32_bf16 v[10:13], v[142:145], v[234:237], v[10:13]
	v_mfma_f32_16x16x32_bf16 v[54:57], v[176:179], v[192:195], v[54:57]
	v_mfma_f32_16x16x32_bf16 v[50:53], v[184:187], v[192:195], v[50:53]
	v_mfma_f32_16x16x32_bf16 v[38:41], v[176:179], v[200:203], v[38:41]
	v_mfma_f32_16x16x32_bf16 v[34:37], v[184:187], v[200:203], v[34:37]
	v_mfma_f32_16x16x32_bf16 v[22:25], v[176:179], v[222:225], v[22:25]
	v_mfma_f32_16x16x32_bf16 v[18:21], v[184:187], v[222:225], v[18:21]
	v_mfma_f32_16x16x32_bf16 v[6:9], v[176:179], v[230:233], v[6:9]
	v_mfma_f32_16x16x32_bf16 v[2:5], v[184:187], v[230:233], v[2:5]
	v_mfma_f32_16x16x32_bf16 v[54:57], v[180:183], v[196:199], v[54:57]
	v_mfma_f32_16x16x32_bf16 v[50:53], v[188:191], v[196:199], v[50:53]
	v_mfma_f32_16x16x32_bf16 v[38:41], v[180:183], v[204:207], v[38:41]
	v_mfma_f32_16x16x32_bf16 v[34:37], v[188:191], v[204:207], v[34:37]
	v_mfma_f32_16x16x32_bf16 v[22:25], v[180:183], v[226:229], v[22:25]
	v_mfma_f32_16x16x32_bf16 v[18:21], v[188:191], v[226:229], v[18:21]
	v_mfma_f32_16x16x32_bf16 v[6:9], v[180:183], v[234:237], v[6:9]
	v_mfma_f32_16x16x32_bf16 v[2:5], v[188:191], v[234:237], v[2:5]
	s_setprio 0
	s_barrier
	s_add_i32 s85, s85, 2
	s_add_u32 s75, s75, 0x100
	s_addc_u32 s84, s84, 0
	s_cmpk_gt_u32 s85, 0x53
	s_mov_b64 s[44:45], s[62:63]
	s_cbranch_scc0 .LBB0_339
	s_and_b64 vcc, exec, s[50:51]
	s_cbranch_vccz .LBB0_342
	s_barrier
